# prefetch block for the next chunk moved to the top of the DN step (more cover for its HBM latency)
# speedup vs baseline: 1.0456x; 1.0043x over previous
; __device__ void dn_item(const Params& p, int l, int item, char* smem, int wv) {
;     ...
;   auto prefetch = [&](int step) {
;     size_t gbase; int tb, Ls;
;     chunk_info(step, gbase, tb, Ls);
;     int tl = tid;
;     asm volatile("" : "+v"(tl));
;     const int rr = tl / 24, seg = tl - rr * 24, part = seg >> 3, s8 = seg & 7;
;     const u16* src = P + (gbase + tb - 2 + rr) * PS + C_QB + part * 384 + h * 64 + s8 * 8;
; #pragma unroll
;     for (int q = 0; q < 7; ++q) {
;       int r = rr + 10 * q;
;       int t = tb - 2 + r;
;       uint4 val = make_uint4(0, 0, 0, 0);
;       if (tl < 240 && r < 68 && t >= 0 && t < Ls) val = *(const uint4*)(src + (size_t)(10 * q) * PS);
;       pre[q] = val;
.LBB0_339:
	v_add_co_u32_e64 v0, s[44:45], s42, 4
	v_readlane_b32 s6, v254, 3
	v_readfirstlane_b32 s43, v0
	s_cmp_eq_u32 s42, 63
	s_cbranch_scc1 .Lpf_skip
	s_add_i32 s6, s42, 5
	s_add_i32 s7, s42, 1
	s_cmp_lt_u32 s43, 3
	s_movk_i32 s36, 0x1000
	s_cselect_b32 s77, 0x100, s36
	v_readlane_b32 s36, v253, 51
	s_cselect_b32 s40, s6, s7
	v_readlane_b32 s7, v253, 44
	v_readlane_b32 s37, v253, 52
	s_cselect_b32 s6, 3, 63
	s_cselect_b32 s37, s7, s37
	v_readlane_b32 s7, v253, 43
	s_cselect_b32 s36, s7, s36
	s_sub_i32 s41, s6, s40
	v_readlane_b32 s6, v253, 40
	v_readlane_b32 s7, v253, 41
	s_and_b64 s[6:7], s[6:7], exec
	s_cselect_b32 s6, s40, s41
	s_lshl_b32 s76, s6, 6
	s_waitcnt vmcnt(4)
	s_lshr_b32 s40, s77, 6
	s_add_i32 s40, s40, -2
	s_lshr_b32 s41, s76, 6
	s_cmp_eq_u32 s41, 0
	s_cbranch_scc1 .Lpf_edge
	s_cmp_gt_u32 s41, s40
	s_cbranch_scc1 .Lpf_edge
	s_add_i32 s6, s36, s76
	s_add_i32 s6, s6, -2
	s_mul_hi_i32 s41, s6, s71
	s_mul_i32 s40, s6, s71
	s_add_u32 s40, s40, s18
	s_addc_u32 s41, s41, s19
	v_readlane_b32 s6, v253, 56
	s_lshl_b32 s6, s6, 1
	s_add_u32 s40, s40, s6
	s_addc_u32 s41, s41, 0
	s_mov_b32 s6, 0x2aaaaaab
	v_mul_hi_i32 v0, v78, s6
	v_lshrrev_b32_e32 v26, 31, v0
	v_ashrrev_i32_e32 v0, 2, v0
	v_add_u32_e32 v0, v0, v26
	v_mul_u32_u24_e32 v26, 24, v0
	v_sub_u32_e32 v26, v78, v26
	v_lshrrev_b32_e32 v27, 3, v26
	v_and_b32_e32 v26, 7, v26
	v_mul_u32_u24_e32 v27, 0x300, v27
	v_lshl_add_u32 v26, v26, 4, v27
	v_mad_u32_u24 v26, v0, s71, v26
	s_movk_i32 s6, 0xf0
	v_cmp_gt_i32_e32 vcc, s6, v78
	s_and_saveexec_b64 s[6:7], vcc
	global_load_dwordx4 v[2:5], v26, s[40:41] offset:1536
	v_add_u32_e32 v27, 0x10400, v26
	global_load_dwordx4 v[6:9], v27, s[40:41] offset:1536
	v_add_u32_e32 v27, 0x20800, v26
	global_load_dwordx4 v[10:13], v27, s[40:41] offset:1536
	v_add_u32_e32 v27, 0x30c00, v26
	global_load_dwordx4 v[14:17], v27, s[40:41] offset:1536
	v_add_u32_e32 v27, 0x41000, v26
	global_load_dwordx4 v[18:21], v27, s[40:41] offset:1536
	v_add_u32_e32 v27, 0x51400, v26
	global_load_dwordx4 v[22:25], v27, s[40:41] offset:1536
	v_cmp_gt_i32_e32 vcc, s14, v78
	v_add_u32_e32 v27, 0x61800, v26
	s_and_b64 exec, exec, vcc
	global_load_dwordx4 v[26:29], v27, s[40:41] offset:1536
	s_or_b64 exec, exec, s[6:7]
	s_branch .Lpf_join

; __device__ void dn_item(const Params& p, int l, int item, char* smem, int wv) {
;     ...
;       const int ti = tid >> 2, dc = tid & 3;
;       const int ip = dir ? 63 - ti : ti;
;       const float ekd = __expf(gcs[63] - gcs[ip]);
; #pragma unroll
;       for (int part = 0; part < 3; ++part) {
;         float acc[16];
; #pragma unroll
;         for (int e = 0; e < 16; ++e) acc[e] = 0.f;
; #pragma unroll
;         for (int kb2 = 0; kb2 < 2; ++kb2) {
;           const int k0 = kb2 * 3, nk = kb2 ? 2 : 3;
;           uint4 rv[3][2];
;           float4 wv4[3][4];
; #pragma unroll
;           for (int kq = 0; kq < 3; ++kq) {
;             if (kq < nk) {
;               const int kk = k0 + kq;
;               const u16* rr = R0 + (ti + kk) * RS + part * 64 + dc * 16;
;               rv[kq][0] = *(const uint4*)rr;
;               rv[kq][1] = *(const uint4*)(rr + 8);
;               const float* wp = cw + kk * 192 + part * 64 + dc * 16;
; #pragma unroll
;               for (int e4 = 0; e4 < 4; ++e4) wv4[kq][e4] = *(const float4*)(wp + e4 * 4);
;             }
;           }
;           __builtin_amdgcn_sched_barrier(0);
; #pragma unroll
;           for (int kq = 0; kq < 3; ++kq) {
;             if (kq < nk) {
;               unsigned rw[8] = {rv[kq][0].x, rv[kq][0].y, rv[kq][0].z, rv[kq][0].w, rv[kq][1].x, rv[kq][1].y, rv[kq][1].z, rv[kq][1].w};
; #pragma unroll
;               for (int e4 = 0; e4 < 4; ++e4) {
;                 float4 w = wv4[kq][e4];
;                 acc[e4 * 4 + 0] += w.x * __uint_as_float(rw[e4 * 2] << 16);
;                 acc[e4 * 4 + 1] += w.y * __uint_as_float(rw[e4 * 2] & 0xffff0000u);
;                 acc[e4 * 4 + 2] += w.z * __uint_as_float(rw[e4 * 2 + 1] << 16);
;                 acc[e4 * 4 + 3] += w.w * __uint_as_float(rw[e4 * 2 + 1] & 0xffff0000u);
;               }
;             }
;           }
;           __builtin_amdgcn_sched_barrier(0);
;         }
.Lpf_skip:
	v_readlane_b32 s6, v254, 3
	s_nop 1
	v_mov_b32_e32 v0, s6
	ds_read_b32 v132, v0
	ds_read_b32 v133, v198
	ds_read_b32 v134, v199
	ds_read_b128 v[30:33], v187 offset:0
	ds_read_b128 v[34:37], v187 offset:400
	ds_read_b128 v[38:41], v187 offset:800
	ds_read_b128 v[42:45], v187 offset:1200
	ds_read_b128 v[46:49], v187 offset:1600
	ds_read_b128 v[50:53], v187 offset:2000
	ds_read_b128 v[54:57], v188 offset:0
	ds_read_b128 v[58:61], v188 offset:16
	ds_read_b128 v[62:65], v188 offset:768
	ds_read_b128 v[66:69], v188 offset:784
	ds_read_b128 v[70:73], v188 offset:1536
	ds_read_b128 v[74:77], v188 offset:1552
	ds_read_b128 v[106:109], v188 offset:2304
	ds_read_b128 v[110:113], v188 offset:2320
	ds_read_b128 v[114:117], v188 offset:3072
	ds_read_b128 v[118:121], v188 offset:3088
	s_mov_b32 s15, 0x800000
	v_mov_b32_e32 v176, 0xbfb8aa3b
	v_mov_b32_e32 v180, 1.0
	s_waitcnt lgkmcnt(10)
	v_lshlrev_b32_e32 v122, 16, v30
	v_and_b32_e32 v123, 0xffff0000, v30
	v_lshlrev_b32_e32 v160, 16, v31
	v_and_b32_e32 v161, 0xffff0000, v31
	v_lshlrev_b32_e32 v124, 16, v34
	v_and_b32_e32 v125, 0xffff0000, v34
	v_lshlrev_b32_e32 v162, 16, v35
	v_and_b32_e32 v163, 0xffff0000, v35
	v_lshlrev_b32_e32 v126, 16, v38
	v_and_b32_e32 v127, 0xffff0000, v38
	v_lshlrev_b32_e32 v164, 16, v39
	v_and_b32_e32 v165, 0xffff0000, v39
	v_lshlrev_b32_e32 v128, 16, v42
	v_and_b32_e32 v129, 0xffff0000, v42
	v_lshlrev_b32_e32 v166, 16, v43
	v_and_b32_e32 v167, 0xffff0000, v43
	v_lshlrev_b32_e32 v140, 16, v46
	v_and_b32_e32 v141, 0xffff0000, v46
	v_lshlrev_b32_e32 v168, 16, v47
	v_and_b32_e32 v169, 0xffff0000, v47
	v_lshlrev_b32_e32 v142, 16, v50
	v_and_b32_e32 v143, 0xffff0000, v50
	v_lshlrev_b32_e32 v170, 16, v51
	v_and_b32_e32 v171, 0xffff0000, v51
	v_sub_f32_e32 v133, v132, v133
	v_sub_f32_e32 v134, v132, v134
	v_mul_f32_e32 v133, 0x3fb8aa3b, v133
	v_mul_f32_e32 v134, 0x3fb8aa3b, v134
	v_exp_f32_e32 v133, v133
	v_exp_f32_e32 v134, v134
	s_waitcnt lgkmcnt(8)
	v_pk_fma_f32 v[144:145], v[54:55], v[122:123], 0 op_sel_hi:[1,1,0]
	v_pk_fma_f32 v[152:153], v[54:55], v[124:125], 0 op_sel_hi:[1,1,0]
	v_pk_fma_f32 v[146:147], v[56:57], v[160:161], 0 op_sel_hi:[1,1,0]
	v_pk_fma_f32 v[154:155], v[56:57], v[162:163], 0 op_sel_hi:[1,1,0]
	s_waitcnt lgkmcnt(6)
	v_pk_fma_f32 v[144:145], v[62:63], v[124:125], v[144:145]
	v_pk_fma_f32 v[152:153], v[62:63], v[126:127], v[152:153]
	v_pk_fma_f32 v[146:147], v[64:65], v[162:163], v[146:147]
	v_pk_fma_f32 v[154:155], v[64:65], v[164:165], v[154:155]
	s_waitcnt lgkmcnt(4)
	v_pk_fma_f32 v[144:145], v[70:71], v[126:127], v[144:145]
	v_pk_fma_f32 v[152:153], v[70:71], v[128:129], v[152:153]
	v_pk_fma_f32 v[146:147], v[72:73], v[164:165], v[146:147]
	v_pk_fma_f32 v[154:155], v[72:73], v[166:167], v[154:155]
	s_waitcnt lgkmcnt(2)
	v_pk_fma_f32 v[144:145], v[106:107], v[128:129], v[144:145]
	v_pk_fma_f32 v[152:153], v[106:107], v[140:141], v[152:153]
	v_pk_fma_f32 v[146:147], v[108:109], v[166:167], v[146:147]
	v_pk_fma_f32 v[154:155], v[108:109], v[168:169], v[154:155]
	s_waitcnt lgkmcnt(0)
	v_pk_fma_f32 v[144:145], v[114:115], v[140:141], v[144:145]
	v_pk_fma_f32 v[152:153], v[114:115], v[142:143], v[152:153]
	v_pk_fma_f32 v[146:147], v[116:117], v[168:169], v[146:147]
	v_pk_fma_f32 v[154:155], v[116:117], v[170:171], v[154:155]
	v_lshlrev_b32_e32 v122, 16, v32
	v_and_b32_e32 v123, 0xffff0000, v32
	v_lshlrev_b32_e32 v160, 16, v33
	v_and_b32_e32 v161, 0xffff0000, v33
	v_lshlrev_b32_e32 v124, 16, v36
	v_and_b32_e32 v125, 0xffff0000, v36
	v_lshlrev_b32_e32 v162, 16, v37
	v_and_b32_e32 v163, 0xffff0000, v37
	v_lshlrev_b32_e32 v126, 16, v40
	v_and_b32_e32 v127, 0xffff0000, v40
	v_lshlrev_b32_e32 v164, 16, v41
	v_and_b32_e32 v165, 0xffff0000, v41
	v_lshlrev_b32_e32 v128, 16, v44
	v_and_b32_e32 v129, 0xffff0000, v44
	v_lshlrev_b32_e32 v166, 16, v45
	v_and_b32_e32 v167, 0xffff0000, v45
	v_lshlrev_b32_e32 v140, 16, v48
	v_and_b32_e32 v141, 0xffff0000, v48
	v_lshlrev_b32_e32 v168, 16, v49
	v_and_b32_e32 v169, 0xffff0000, v49
	v_lshlrev_b32_e32 v142, 16, v52
	v_and_b32_e32 v143, 0xffff0000, v52
	v_lshlrev_b32_e32 v170, 16, v53
	v_and_b32_e32 v171, 0xffff0000, v53
	v_pk_fma_f32 v[148:149], v[58:59], v[122:123], 0 op_sel_hi:[1,1,0]
	v_pk_fma_f32 v[156:157], v[58:59], v[124:125], 0 op_sel_hi:[1,1,0]
	v_pk_fma_f32 v[150:151], v[60:61], v[160:161], 0 op_sel_hi:[1,1,0]
	v_pk_fma_f32 v[158:159], v[60:61], v[162:163], 0 op_sel_hi:[1,1,0]
	v_pk_fma_f32 v[148:149], v[66:67], v[124:125], v[148:149]
	v_pk_fma_f32 v[156:157], v[66:67], v[126:127], v[156:157]
	v_pk_fma_f32 v[150:151], v[68:69], v[162:163], v[150:151]
	v_pk_fma_f32 v[158:159], v[68:69], v[164:165], v[158:159]
	v_pk_fma_f32 v[148:149], v[74:75], v[126:127], v[148:149]
	v_pk_fma_f32 v[156:157], v[74:75], v[128:129], v[156:157]
	v_pk_fma_f32 v[150:151], v[76:77], v[164:165], v[150:151]
	v_pk_fma_f32 v[158:159], v[76:77], v[166:167], v[158:159]
	v_pk_fma_f32 v[148:149], v[110:111], v[128:129], v[148:149]
	v_pk_fma_f32 v[156:157], v[110:111], v[140:141], v[156:157]
	v_pk_fma_f32 v[150:151], v[112:113], v[166:167], v[150:151]
	v_pk_fma_f32 v[158:159], v[112:113], v[168:169], v[158:159]
	v_pk_fma_f32 v[148:149], v[118:119], v[140:141], v[148:149]
	v_pk_fma_f32 v[156:157], v[118:119], v[142:143], v[156:157]
	v_pk_fma_f32 v[150:151], v[120:121], v[168:169], v[150:151]
	v_pk_fma_f32 v[158:159], v[120:121], v[170:171], v[158:159]
	ds_read_b128 v[30:33], v187 offset:128
	ds_read_b128 v[34:37], v187 offset:528
	ds_read_b128 v[38:41], v187 offset:928
	ds_read_b128 v[42:45], v187 offset:1328
	ds_read_b128 v[46:49], v187 offset:1728
	ds_read_b128 v[50:53], v187 offset:2128
	ds_read_b128 v[54:57], v188 offset:256
; __device__ __forceinline__ float siluf_(float x) { return x * __builtin_amdgcn_rcpf(1.f + __expf(-x)); }
; __device__ void dn_item(const Params& p, int l, int item, char* smem, int wv) {
;     ...
;         float ss = 0.f;
; #pragma unroll
;         for (int e = 0; e < 16; ++e) { acc[e] = siluf_(acc[e]); ss += acc[e] * acc[e]; }
;         float sc = 1.f;
;         if (part < 2) {
;           ss += shx(ss, 1, lane);
;           ss += shx(ss, 2, lane);
;           sc = rsqrtf(ss + 1e-6f) * (part == 0 ? 0.125f : 1.f);
;         }
; #pragma unroll
;         for (int e = 0; e < 16; ++e) acc[e] *= sc;
;         u16* dst = (part == 0 ? Qb : (part == 1 ? Kb : Vb)) + ip * 72 + dc * 16;
;         *(uint4*)dst = make_uint4(pack2(acc[0], acc[1]), pack2(acc[2], acc[3]), pack2(acc[4], acc[5]), pack2(acc[6], acc[7]));
;         *(uint4*)(dst + 8) = make_uint4(pack2(acc[8], acc[9]), pack2(acc[10], acc[11]), pack2(acc[12], acc[13]), pack2(acc[14], acc[15]));
	ds_read_b128 v[58:61], v188 offset:272
	ds_read_b128 v[62:65], v188 offset:1024
	ds_read_b128 v[66:69], v188 offset:1040
	ds_read_b128 v[70:73], v188 offset:1792
	ds_read_b128 v[74:77], v188 offset:1808
	ds_read_b128 v[106:109], v188 offset:2560
	ds_read_b128 v[110:113], v188 offset:2576
	ds_read_b128 v[114:117], v188 offset:3328
	ds_read_b128 v[118:121], v188 offset:3344
	v_pk_mul_f32 v[160:161], v[144:145], v[176:177] op_sel_hi:[1,0]
	v_pk_mul_f32 v[162:163], v[146:147], v[176:177] op_sel_hi:[1,0]
	v_pk_mul_f32 v[164:165], v[148:149], v[176:177] op_sel_hi:[1,0]
	v_pk_mul_f32 v[166:167], v[150:151], v[176:177] op_sel_hi:[1,0]
	v_pk_mul_f32 v[168:169], v[152:153], v[176:177] op_sel_hi:[1,0]
	v_pk_mul_f32 v[170:171], v[154:155], v[176:177] op_sel_hi:[1,0]
	v_pk_mul_f32 v[172:173], v[156:157], v[176:177] op_sel_hi:[1,0]
	v_pk_mul_f32 v[174:175], v[158:159], v[176:177] op_sel_hi:[1,0]
	v_exp_f32_e32 v160, v160
	v_exp_f32_e32 v161, v161
	v_exp_f32_e32 v162, v162
	v_exp_f32_e32 v163, v163
	v_exp_f32_e32 v164, v164
	v_exp_f32_e32 v165, v165
	v_exp_f32_e32 v166, v166
	v_exp_f32_e32 v167, v167
	v_exp_f32_e32 v168, v168
	v_exp_f32_e32 v169, v169
	v_exp_f32_e32 v170, v170
	v_exp_f32_e32 v171, v171
	v_exp_f32_e32 v172, v172
	v_exp_f32_e32 v173, v173
	v_exp_f32_e32 v174, v174
	v_exp_f32_e32 v175, v175
	v_pk_add_f32 v[160:161], v[160:161], v[180:181] op_sel_hi:[1,0]
	v_pk_add_f32 v[162:163], v[162:163], v[180:181] op_sel_hi:[1,0]
	v_pk_add_f32 v[164:165], v[164:165], v[180:181] op_sel_hi:[1,0]
	v_pk_add_f32 v[166:167], v[166:167], v[180:181] op_sel_hi:[1,0]
	v_pk_add_f32 v[168:169], v[168:169], v[180:181] op_sel_hi:[1,0]
	v_pk_add_f32 v[170:171], v[170:171], v[180:181] op_sel_hi:[1,0]
	v_pk_add_f32 v[172:173], v[172:173], v[180:181] op_sel_hi:[1,0]
	v_pk_add_f32 v[174:175], v[174:175], v[180:181] op_sel_hi:[1,0]
	v_rcp_f32_e32 v160, v160
	v_rcp_f32_e32 v161, v161
	v_rcp_f32_e32 v162, v162
	v_rcp_f32_e32 v163, v163
	v_rcp_f32_e32 v164, v164
	v_rcp_f32_e32 v165, v165
	v_rcp_f32_e32 v166, v166
	v_rcp_f32_e32 v167, v167
	v_rcp_f32_e32 v168, v168
	v_rcp_f32_e32 v169, v169
	v_rcp_f32_e32 v170, v170
	v_rcp_f32_e32 v171, v171
	v_rcp_f32_e32 v172, v172
	v_rcp_f32_e32 v173, v173
	v_rcp_f32_e32 v174, v174
	v_rcp_f32_e32 v175, v175
	s_nop 0
	v_pk_mul_f32 v[144:145], v[144:145], v[160:161]
	v_pk_mul_f32 v[146:147], v[146:147], v[162:163]
	v_pk_mul_f32 v[148:149], v[148:149], v[164:165]
	v_pk_mul_f32 v[150:151], v[150:151], v[166:167]
	v_pk_mul_f32 v[152:153], v[152:153], v[168:169]
	v_pk_mul_f32 v[154:155], v[154:155], v[170:171]
	v_pk_mul_f32 v[156:157], v[156:157], v[172:173]
	v_pk_mul_f32 v[158:159], v[158:159], v[174:175]
	v_pk_mul_f32 v[160:161], v[144:145], v[144:145]
	v_pk_mul_f32 v[162:163], v[146:147], v[146:147]
	v_pk_mul_f32 v[164:165], v[148:149], v[148:149]
	v_pk_mul_f32 v[166:167], v[150:151], v[150:151]
	v_pk_mul_f32 v[168:169], v[152:153], v[152:153]
	v_pk_mul_f32 v[170:171], v[154:155], v[154:155]
	v_pk_mul_f32 v[172:173], v[156:157], v[156:157]
	v_pk_mul_f32 v[174:175], v[158:159], v[158:159]
	v_pk_add_f32 v[160:161], v[160:161], v[162:163]
	v_pk_add_f32 v[164:165], v[164:165], v[166:167]
	v_pk_add_f32 v[168:169], v[168:169], v[170:171]
	v_pk_add_f32 v[172:173], v[172:173], v[174:175]
	v_pk_add_f32 v[160:161], v[160:161], v[164:165]
	v_pk_add_f32 v[168:169], v[168:169], v[172:173]
	v_add_f32_e32 v136, v160, v161
	v_add_f32_e32 v138, v168, v169
	s_nop 1
	v_add_f32_dpp v135, v136, v136 quad_perm:[1,0,3,2] row_mask:0xf bank_mask:0xf
	v_add_f32_dpp v137, v138, v138 quad_perm:[1,0,3,2] row_mask:0xf bank_mask:0xf
	s_nop 1
	v_add_f32_dpp v136, v135, v135 quad_perm:[2,3,0,1] row_mask:0xf bank_mask:0xf
	v_add_f32_dpp v138, v137, v137 quad_perm:[2,3,0,1] row_mask:0xf bank_mask:0xf
	s_nop 1
	v_add_f32_dpp v135, v136, v136 row_half_mirror row_mask:0xf bank_mask:0xf
	v_add_f32_dpp v137, v138, v138 row_half_mirror row_mask:0xf bank_mask:0xf
	v_add_f32_e32 v136, 0x358637bd, v135
	v_cmp_gt_f32_e32 vcc, s15, v136
	v_mul_f32_e32 v139, 0x4b800000, v136
	s_nop 0
	v_cndmask_b32_e32 v136, v136, v139, vcc
	v_rsq_f32_e32 v136, v136
	s_nop 0
	v_mul_f32_e32 v139, 0x45800000, v136
	v_cndmask_b32_e32 v136, v136, v139, vcc
	v_mul_f32_e32 v136, 0x3e000000, v136
	v_add_f32_e32 v138, 0x358637bd, v137
	v_cmp_gt_f32_e32 vcc, s15, v138
	v_mul_f32_e32 v139, 0x4b800000, v138
	s_nop 0
	v_cndmask_b32_e32 v138, v138, v139, vcc
	v_rsq_f32_e32 v138, v138
	s_nop 0
	v_mul_f32_e32 v139, 0x45800000, v138
	v_cndmask_b32_e32 v138, v138, v139, vcc
	v_mul_f32_e32 v138, 0x3e000000, v138
	v_pk_mul_f32 v[144:145], v[144:145], v[136:137] op_sel_hi:[1,0]
	v_pk_mul_f32 v[146:147], v[146:147], v[136:137] op_sel_hi:[1,0]
	v_pk_mul_f32 v[148:149], v[148:149], v[136:137] op_sel_hi:[1,0]
	v_pk_mul_f32 v[150:151], v[150:151], v[136:137] op_sel_hi:[1,0]
	v_pk_mul_f32 v[152:153], v[152:153], v[138:139] op_sel_hi:[1,0]
	v_pk_mul_f32 v[154:155], v[154:155], v[138:139] op_sel_hi:[1,0]
	v_pk_mul_f32 v[156:157], v[156:157], v[138:139] op_sel_hi:[1,0]
	v_pk_mul_f32 v[158:159], v[158:159], v[138:139] op_sel_hi:[1,0]
	v_cvt_pk_bf16_f32 v172, v144, v145
	v_cvt_pk_bf16_f32 v173, v146, v147
	v_cvt_pk_bf16_f32 v174, v148, v149
	v_cvt_pk_bf16_f32 v175, v150, v151
	ds_write_b128 v195, v[172:175] offset:45632
	v_cvt_pk_bf16_f32 v136, v152, v153
	v_cvt_pk_bf16_f32 v137, v154, v155
	v_cvt_pk_bf16_f32 v138, v156, v157
	v_cvt_pk_bf16_f32 v139, v158, v159
	ds_write_b128 v196, v[136:139] offset:45632
	s_waitcnt lgkmcnt(2)
; __device__ void dn_item(const Params& p, int l, int item, char* smem, int wv) {
;     ...
;         for (int kb2 = 0; kb2 < 2; ++kb2) {
;           const int k0 = kb2 * 3, nk = kb2 ? 2 : 3;
;           uint4 rv[3][2];
;           float4 wv4[3][4];
; #pragma unroll
;           for (int kq = 0; kq < 3; ++kq) {
;             if (kq < nk) {
;               const int kk = k0 + kq;
;               const u16* rr = R0 + (ti + kk) * RS + part * 64 + dc * 16;
;               rv[kq][0] = *(const uint4*)rr;
;               rv[kq][1] = *(const uint4*)(rr + 8);
;               const float* wp = cw + kk * 192 + part * 64 + dc * 16;
; #pragma unroll
;               for (int e4 = 0; e4 < 4; ++e4) wv4[kq][e4] = *(const float4*)(wp + e4 * 4);
;             }
;           }
;           __builtin_amdgcn_sched_barrier(0);
; #pragma unroll
;           for (int kq = 0; kq < 3; ++kq) {
;             if (kq < nk) {
;               unsigned rw[8] = {rv[kq][0].x, rv[kq][0].y, rv[kq][0].z, rv[kq][0].w, rv[kq][1].x, rv[kq][1].y, rv[kq][1].z, rv[kq][1].w};
; #pragma unroll
;               for (int e4 = 0; e4 < 4; ++e4) {
;                 float4 w = wv4[kq][e4];
;                 acc[e4 * 4 + 0] += w.x * __uint_as_float(rw[e4 * 2] << 16);
;                 acc[e4 * 4 + 1] += w.y * __uint_as_float(rw[e4 * 2] & 0xffff0000u);
;                 acc[e4 * 4 + 2] += w.z * __uint_as_float(rw[e4 * 2 + 1] << 16);
;                 acc[e4 * 4 + 3] += w.w * __uint_as_float(rw[e4 * 2 + 1] & 0xffff0000u);
;               }
;             }
;           }
;           __builtin_amdgcn_sched_barrier(0);
;         }
	v_lshlrev_b32_e32 v122, 16, v30
	v_and_b32_e32 v123, 0xffff0000, v30
	v_lshlrev_b32_e32 v160, 16, v31
	v_and_b32_e32 v161, 0xffff0000, v31
	v_lshlrev_b32_e32 v124, 16, v34
	v_and_b32_e32 v125, 0xffff0000, v34
	v_lshlrev_b32_e32 v162, 16, v35
	v_and_b32_e32 v163, 0xffff0000, v35
	v_lshlrev_b32_e32 v126, 16, v38
	v_and_b32_e32 v127, 0xffff0000, v38
	v_lshlrev_b32_e32 v164, 16, v39
	v_and_b32_e32 v165, 0xffff0000, v39
	v_lshlrev_b32_e32 v128, 16, v42
	v_and_b32_e32 v129, 0xffff0000, v42
	v_lshlrev_b32_e32 v166, 16, v43
	v_and_b32_e32 v167, 0xffff0000, v43
	v_lshlrev_b32_e32 v140, 16, v46
	v_and_b32_e32 v141, 0xffff0000, v46
	v_lshlrev_b32_e32 v168, 16, v47
	v_and_b32_e32 v169, 0xffff0000, v47
	v_lshlrev_b32_e32 v142, 16, v50
	v_and_b32_e32 v143, 0xffff0000, v50
	v_lshlrev_b32_e32 v170, 16, v51
	v_and_b32_e32 v171, 0xffff0000, v51
	v_pk_fma_f32 v[144:145], v[54:55], v[122:123], 0 op_sel_hi:[1,1,0]
	v_pk_fma_f32 v[152:153], v[54:55], v[124:125], 0 op_sel_hi:[1,1,0]
	v_pk_fma_f32 v[146:147], v[56:57], v[160:161], 0 op_sel_hi:[1,1,0]
	v_pk_fma_f32 v[154:155], v[56:57], v[162:163], 0 op_sel_hi:[1,1,0]
	v_pk_fma_f32 v[144:145], v[62:63], v[124:125], v[144:145]
	v_pk_fma_f32 v[152:153], v[62:63], v[126:127], v[152:153]
	v_pk_fma_f32 v[146:147], v[64:65], v[162:163], v[146:147]
	v_pk_fma_f32 v[154:155], v[64:65], v[164:165], v[154:155]
	v_pk_fma_f32 v[144:145], v[70:71], v[126:127], v[144:145]
	v_pk_fma_f32 v[152:153], v[70:71], v[128:129], v[152:153]
	v_pk_fma_f32 v[146:147], v[72:73], v[164:165], v[146:147]
	v_pk_fma_f32 v[154:155], v[72:73], v[166:167], v[154:155]
	v_pk_fma_f32 v[144:145], v[106:107], v[128:129], v[144:145]
	v_pk_fma_f32 v[152:153], v[106:107], v[140:141], v[152:153]
	v_pk_fma_f32 v[146:147], v[108:109], v[166:167], v[146:147]
	v_pk_fma_f32 v[154:155], v[108:109], v[168:169], v[154:155]
	v_pk_fma_f32 v[144:145], v[114:115], v[140:141], v[144:145]
	v_pk_fma_f32 v[152:153], v[114:115], v[142:143], v[152:153]
	v_pk_fma_f32 v[146:147], v[116:117], v[168:169], v[146:147]
	v_pk_fma_f32 v[154:155], v[116:117], v[170:171], v[154:155]
	v_lshlrev_b32_e32 v122, 16, v32
	v_and_b32_e32 v123, 0xffff0000, v32
	v_lshlrev_b32_e32 v160, 16, v33
	v_and_b32_e32 v161, 0xffff0000, v33
	v_lshlrev_b32_e32 v124, 16, v36
	v_and_b32_e32 v125, 0xffff0000, v36
	v_lshlrev_b32_e32 v162, 16, v37
	v_and_b32_e32 v163, 0xffff0000, v37
	v_lshlrev_b32_e32 v126, 16, v40
	v_and_b32_e32 v127, 0xffff0000, v40
	v_lshlrev_b32_e32 v164, 16, v41
	v_and_b32_e32 v165, 0xffff0000, v41
	v_lshlrev_b32_e32 v128, 16, v44
	v_and_b32_e32 v129, 0xffff0000, v44
	v_lshlrev_b32_e32 v166, 16, v45
	v_and_b32_e32 v167, 0xffff0000, v45
	v_lshlrev_b32_e32 v140, 16, v48
	v_and_b32_e32 v141, 0xffff0000, v48
	v_lshlrev_b32_e32 v168, 16, v49
	v_and_b32_e32 v169, 0xffff0000, v49
	v_lshlrev_b32_e32 v142, 16, v52
	v_and_b32_e32 v143, 0xffff0000, v52
	v_lshlrev_b32_e32 v170, 16, v53
	v_and_b32_e32 v171, 0xffff0000, v53
	v_pk_fma_f32 v[148:149], v[58:59], v[122:123], 0 op_sel_hi:[1,1,0]
	v_pk_fma_f32 v[156:157], v[58:59], v[124:125], 0 op_sel_hi:[1,1,0]
	v_pk_fma_f32 v[150:151], v[60:61], v[160:161], 0 op_sel_hi:[1,1,0]
	v_pk_fma_f32 v[158:159], v[60:61], v[162:163], 0 op_sel_hi:[1,1,0]
	v_pk_fma_f32 v[148:149], v[66:67], v[124:125], v[148:149]
	v_pk_fma_f32 v[156:157], v[66:67], v[126:127], v[156:157]
	v_pk_fma_f32 v[150:151], v[68:69], v[162:163], v[150:151]
	v_pk_fma_f32 v[158:159], v[68:69], v[164:165], v[158:159]
	v_pk_fma_f32 v[148:149], v[74:75], v[126:127], v[148:149]
	v_pk_fma_f32 v[156:157], v[74:75], v[128:129], v[156:157]
	v_pk_fma_f32 v[150:151], v[76:77], v[164:165], v[150:151]
	v_pk_fma_f32 v[158:159], v[76:77], v[166:167], v[158:159]
	v_pk_fma_f32 v[148:149], v[110:111], v[128:129], v[148:149]
	v_pk_fma_f32 v[156:157], v[110:111], v[140:141], v[156:157]
	v_pk_fma_f32 v[150:151], v[112:113], v[166:167], v[150:151]
	v_pk_fma_f32 v[158:159], v[112:113], v[168:169], v[158:159]
	v_pk_fma_f32 v[148:149], v[118:119], v[140:141], v[148:149]
	v_pk_fma_f32 v[156:157], v[118:119], v[142:143], v[156:157]
	v_pk_fma_f32 v[150:151], v[120:121], v[168:169], v[150:151]
	v_pk_fma_f32 v[158:159], v[120:121], v[170:171], v[158:159]
	ds_read_b128 v[30:33], v187 offset:256
	ds_read_b128 v[34:37], v187 offset:656
	ds_read_b128 v[38:41], v187 offset:1056
	ds_read_b128 v[42:45], v187 offset:1456
	ds_read_b128 v[46:49], v187 offset:1856
	ds_read_b128 v[50:53], v187 offset:2256
	ds_read_b128 v[54:57], v188 offset:512
	ds_read_b128 v[58:61], v188 offset:528
	ds_read_b128 v[62:65], v188 offset:1280
	ds_read_b128 v[66:69], v188 offset:1296
	ds_read_b128 v[70:73], v188 offset:2048
	ds_read_b128 v[74:77], v188 offset:2064
	ds_read_b128 v[106:109], v188 offset:2816
	ds_read_b128 v[110:113], v188 offset:2832
	ds_read_b128 v[114:117], v188 offset:3584
	ds_read_b128 v[118:121], v188 offset:3600
	v_pk_mul_f32 v[160:161], v[144:145], v[176:177] op_sel_hi:[1,0]
	v_pk_mul_f32 v[162:163], v[146:147], v[176:177] op_sel_hi:[1,0]
	v_pk_mul_f32 v[164:165], v[148:149], v[176:177] op_sel_hi:[1,0]
	v_pk_mul_f32 v[166:167], v[150:151], v[176:177] op_sel_hi:[1,0]
	v_pk_mul_f32 v[168:169], v[152:153], v[176:177] op_sel_hi:[1,0]
	v_pk_mul_f32 v[170:171], v[154:155], v[176:177] op_sel_hi:[1,0]
; __device__ __forceinline__ u16 f2bf(float f) { return (u16)(pack2(f, 0.f) & 0xffffu); }
; __device__ __forceinline__ float siluf_(float x) { return x * __builtin_amdgcn_rcpf(1.f + __expf(-x)); }
; __device__ void dn_item(const Params& p, int l, int item, char* smem, int wv) {
;     ...
;         float ss = 0.f;
; #pragma unroll
;         for (int e = 0; e < 16; ++e) { acc[e] = siluf_(acc[e]); ss += acc[e] * acc[e]; }
;         float sc = 1.f;
;         if (part < 2) {
;           ss += shx(ss, 1, lane);
;           ss += shx(ss, 2, lane);
;           sc = rsqrtf(ss + 1e-6f) * (part == 0 ? 0.125f : 1.f);
;         }
; #pragma unroll
;         for (int e = 0; e < 16; ++e) acc[e] *= sc;
;         u16* dst = (part == 0 ? Qb : (part == 1 ? Kb : Vb)) + ip * 72 + dc * 16;
;         *(uint4*)dst = make_uint4(pack2(acc[0], acc[1]), pack2(acc[2], acc[3]), pack2(acc[4], acc[5]), pack2(acc[6], acc[7]));
;         *(uint4*)(dst + 8) = make_uint4(pack2(acc[8], acc[9]), pack2(acc[10], acc[11]), pack2(acc[12], acc[13]), pack2(acc[14], acc[15]));
;         if (part == 1) {
; #pragma unroll
;           for (int e = 0; e < 16; ++e) KdT[(dc * 16 + e) * 72 + ip] = f2bf(acc[e] * ekd);
	v_pk_mul_f32 v[172:173], v[156:157], v[176:177] op_sel_hi:[1,0]
	v_pk_mul_f32 v[174:175], v[158:159], v[176:177] op_sel_hi:[1,0]
	v_exp_f32_e32 v160, v160
	v_exp_f32_e32 v161, v161
	v_exp_f32_e32 v162, v162
	v_exp_f32_e32 v163, v163
	v_exp_f32_e32 v164, v164
	v_exp_f32_e32 v165, v165
	v_exp_f32_e32 v166, v166
	v_exp_f32_e32 v167, v167
	v_exp_f32_e32 v168, v168
	v_exp_f32_e32 v169, v169
	v_exp_f32_e32 v170, v170
	v_exp_f32_e32 v171, v171
	v_exp_f32_e32 v172, v172
	v_exp_f32_e32 v173, v173
	v_exp_f32_e32 v174, v174
	v_exp_f32_e32 v175, v175
	v_pk_add_f32 v[160:161], v[160:161], v[180:181] op_sel_hi:[1,0]
	v_pk_add_f32 v[162:163], v[162:163], v[180:181] op_sel_hi:[1,0]
	v_pk_add_f32 v[164:165], v[164:165], v[180:181] op_sel_hi:[1,0]
	v_pk_add_f32 v[166:167], v[166:167], v[180:181] op_sel_hi:[1,0]
	v_pk_add_f32 v[168:169], v[168:169], v[180:181] op_sel_hi:[1,0]
	v_pk_add_f32 v[170:171], v[170:171], v[180:181] op_sel_hi:[1,0]
	v_pk_add_f32 v[172:173], v[172:173], v[180:181] op_sel_hi:[1,0]
	v_pk_add_f32 v[174:175], v[174:175], v[180:181] op_sel_hi:[1,0]
	v_rcp_f32_e32 v160, v160
	v_rcp_f32_e32 v161, v161
	v_rcp_f32_e32 v162, v162
	v_rcp_f32_e32 v163, v163
	v_rcp_f32_e32 v164, v164
	v_rcp_f32_e32 v165, v165
	v_rcp_f32_e32 v166, v166
	v_rcp_f32_e32 v167, v167
	v_rcp_f32_e32 v168, v168
	v_rcp_f32_e32 v169, v169
	v_rcp_f32_e32 v170, v170
	v_rcp_f32_e32 v171, v171
	v_rcp_f32_e32 v172, v172
	v_rcp_f32_e32 v173, v173
	v_rcp_f32_e32 v174, v174
	v_rcp_f32_e32 v175, v175
	s_nop 0
	v_pk_mul_f32 v[144:145], v[144:145], v[160:161]
	v_pk_mul_f32 v[146:147], v[146:147], v[162:163]
	v_pk_mul_f32 v[148:149], v[148:149], v[164:165]
	v_pk_mul_f32 v[150:151], v[150:151], v[166:167]
	v_pk_mul_f32 v[152:153], v[152:153], v[168:169]
	v_pk_mul_f32 v[154:155], v[154:155], v[170:171]
	v_pk_mul_f32 v[156:157], v[156:157], v[172:173]
	v_pk_mul_f32 v[158:159], v[158:159], v[174:175]
	v_pk_mul_f32 v[160:161], v[144:145], v[144:145]
	v_pk_mul_f32 v[162:163], v[146:147], v[146:147]
	v_pk_mul_f32 v[164:165], v[148:149], v[148:149]
	v_pk_mul_f32 v[166:167], v[150:151], v[150:151]
	v_pk_mul_f32 v[168:169], v[152:153], v[152:153]
	v_pk_mul_f32 v[170:171], v[154:155], v[154:155]
	v_pk_mul_f32 v[172:173], v[156:157], v[156:157]
	v_pk_mul_f32 v[174:175], v[158:159], v[158:159]
	v_pk_add_f32 v[160:161], v[160:161], v[162:163]
	v_pk_add_f32 v[164:165], v[164:165], v[166:167]
	v_pk_add_f32 v[168:169], v[168:169], v[170:171]
	v_pk_add_f32 v[172:173], v[172:173], v[174:175]
	v_pk_add_f32 v[160:161], v[160:161], v[164:165]
	v_pk_add_f32 v[168:169], v[168:169], v[172:173]
	v_add_f32_e32 v136, v160, v161
	v_add_f32_e32 v138, v168, v169
	s_nop 1
	v_add_f32_dpp v135, v136, v136 quad_perm:[1,0,3,2] row_mask:0xf bank_mask:0xf
	v_add_f32_dpp v137, v138, v138 quad_perm:[1,0,3,2] row_mask:0xf bank_mask:0xf
	s_nop 1
	v_add_f32_dpp v136, v135, v135 quad_perm:[2,3,0,1] row_mask:0xf bank_mask:0xf
	v_add_f32_dpp v138, v137, v137 quad_perm:[2,3,0,1] row_mask:0xf bank_mask:0xf
	s_nop 1
	v_add_f32_dpp v135, v136, v136 row_half_mirror row_mask:0xf bank_mask:0xf
	v_add_f32_dpp v137, v138, v138 row_half_mirror row_mask:0xf bank_mask:0xf
	v_add_f32_e32 v136, 0x358637bd, v135
	v_cmp_gt_f32_e32 vcc, s15, v136
	v_mul_f32_e32 v139, 0x4b800000, v136
	s_nop 0
	v_cndmask_b32_e32 v136, v136, v139, vcc
	v_rsq_f32_e32 v136, v136
	s_nop 0
	v_mul_f32_e32 v139, 0x45800000, v136
	v_cndmask_b32_e32 v136, v136, v139, vcc
	v_add_f32_e32 v138, 0x358637bd, v137
	v_cmp_gt_f32_e32 vcc, s15, v138
	v_mul_f32_e32 v139, 0x4b800000, v138
	s_nop 0
	v_cndmask_b32_e32 v138, v138, v139, vcc
	v_rsq_f32_e32 v138, v138
	s_nop 0
	v_mul_f32_e32 v139, 0x45800000, v138
	v_cndmask_b32_e32 v138, v138, v139, vcc
	v_pk_mul_f32 v[144:145], v[144:145], v[136:137] op_sel_hi:[1,0]
	v_pk_mul_f32 v[146:147], v[146:147], v[136:137] op_sel_hi:[1,0]
	v_pk_mul_f32 v[148:149], v[148:149], v[136:137] op_sel_hi:[1,0]
	v_pk_mul_f32 v[150:151], v[150:151], v[136:137] op_sel_hi:[1,0]
	v_pk_mul_f32 v[152:153], v[152:153], v[138:139] op_sel_hi:[1,0]
	v_pk_mul_f32 v[154:155], v[154:155], v[138:139] op_sel_hi:[1,0]
	v_pk_mul_f32 v[156:157], v[156:157], v[138:139] op_sel_hi:[1,0]
	v_pk_mul_f32 v[158:159], v[158:159], v[138:139] op_sel_hi:[1,0]
	v_pk_mul_f32 v[122:123], v[144:145], v[132:133] op_sel:[0,1] op_sel_hi:[1,1]
	v_pk_mul_f32 v[140:141], v[152:153], v[134:135] op_sel_hi:[1,0]
	v_pk_mul_f32 v[124:125], v[146:147], v[132:133] op_sel:[0,1] op_sel_hi:[1,1]
	v_pk_mul_f32 v[142:143], v[154:155], v[134:135] op_sel_hi:[1,0]
	v_pk_mul_f32 v[126:127], v[148:149], v[132:133] op_sel:[0,1] op_sel_hi:[1,1]
	v_pk_mul_f32 v[160:161], v[156:157], v[134:135] op_sel_hi:[1,0]
	v_pk_mul_f32 v[128:129], v[150:151], v[132:133] op_sel:[0,1] op_sel_hi:[1,1]
	v_pk_mul_f32 v[162:163], v[158:159], v[134:135] op_sel_hi:[1,0]
	v_readlane_b32 s6, v253, 40
	s_cmp_lg_u32 s6, 0
	s_cbranch_scc0 .Lb_kdt_dir1
	v_cvt_pk_bf16_f32 v164, v122, v140
	v_cvt_pk_bf16_f32 v165, v123, v141
	v_cvt_pk_bf16_f32 v166, v124, v142
	v_cvt_pk_bf16_f32 v167, v125, v143
	v_cvt_pk_bf16_f32 v168, v126, v160
	v_cvt_pk_bf16_f32 v169, v127, v161
	v_cvt_pk_bf16_f32 v170, v128, v162
	v_cvt_pk_bf16_f32 v171, v129, v163
	s_branch .Lb_kdt_st

; __device__ __forceinline__ u16 f2bf(float f) { return (u16)(pack2(f, 0.f) & 0xffffu); }
; __device__ void dn_item(const Params& p, int l, int item, char* smem, int wv) {
;     ...
;         for (int kb2 = 0; kb2 < 2; ++kb2) {
;           const int k0 = kb2 * 3, nk = kb2 ? 2 : 3;
;           uint4 rv[3][2];
;           float4 wv4[3][4];
; #pragma unroll
;           for (int kq = 0; kq < 3; ++kq) {
;             if (kq < nk) {
;               const int kk = k0 + kq;
;               const u16* rr = R0 + (ti + kk) * RS + part * 64 + dc * 16;
;               rv[kq][0] = *(const uint4*)rr;
;               rv[kq][1] = *(const uint4*)(rr + 8);
;               const float* wp = cw + kk * 192 + part * 64 + dc * 16;
; #pragma unroll
;               for (int e4 = 0; e4 < 4; ++e4) wv4[kq][e4] = *(const float4*)(wp + e4 * 4);
;             }
;           }
;           __builtin_amdgcn_sched_barrier(0);
; #pragma unroll
;           for (int kq = 0; kq < 3; ++kq) {
;             if (kq < nk) {
;               unsigned rw[8] = {rv[kq][0].x, rv[kq][0].y, rv[kq][0].z, rv[kq][0].w, rv[kq][1].x, rv[kq][1].y, rv[kq][1].z, rv[kq][1].w};
; #pragma unroll
;               for (int e4 = 0; e4 < 4; ++e4) {
;                 float4 w = wv4[kq][e4];
;                 acc[e4 * 4 + 0] += w.x * __uint_as_float(rw[e4 * 2] << 16);
;                 acc[e4 * 4 + 1] += w.y * __uint_as_float(rw[e4 * 2] & 0xffff0000u);
;                 acc[e4 * 4 + 2] += w.z * __uint_as_float(rw[e4 * 2 + 1] << 16);
;                 acc[e4 * 4 + 3] += w.w * __uint_as_float(rw[e4 * 2 + 1] & 0xffff0000u);
;               }
;             }
;           }
;           __builtin_amdgcn_sched_barrier(0);
;         }
;     ...
;         u16* dst = (part == 0 ? Qb : (part == 1 ? Kb : Vb)) + ip * 72 + dc * 16;
;         *(uint4*)dst = make_uint4(pack2(acc[0], acc[1]), pack2(acc[2], acc[3]), pack2(acc[4], acc[5]), pack2(acc[6], acc[7]));
;         *(uint4*)(dst + 8) = make_uint4(pack2(acc[8], acc[9]), pack2(acc[10], acc[11]), pack2(acc[12], acc[13]), pack2(acc[14], acc[15]));
;         if (part == 1) {
; #pragma unroll
;           for (int e = 0; e < 16; ++e) KdT[(dc * 16 + e) * 72 + ip] = f2bf(acc[e] * ekd);
.Lb_kdt_st:
	ds_write_b32 v197, v164 offset:0
	ds_write_b32 v197, v165 offset:144
	ds_write_b32 v197, v166 offset:288
	ds_write_b32 v197, v167 offset:432
	ds_write_b32 v197, v168 offset:576
	ds_write_b32 v197, v169 offset:720
	ds_write_b32 v197, v170 offset:864
	ds_write_b32 v197, v171 offset:1008
	v_cvt_pk_bf16_f32 v172, v144, v145
	v_cvt_pk_bf16_f32 v173, v146, v147
	v_cvt_pk_bf16_f32 v174, v148, v149
	v_cvt_pk_bf16_f32 v175, v150, v151
	ds_write_b128 v195, v[172:175] offset:27200
	v_cvt_pk_bf16_f32 v136, v152, v153
	v_cvt_pk_bf16_f32 v137, v154, v155
	v_cvt_pk_bf16_f32 v138, v156, v157
	v_cvt_pk_bf16_f32 v139, v158, v159
	ds_write_b128 v196, v[136:139] offset:27200
	s_waitcnt lgkmcnt(10)
	v_lshlrev_b32_e32 v122, 16, v30
	v_and_b32_e32 v123, 0xffff0000, v30
	v_lshlrev_b32_e32 v160, 16, v31
	v_and_b32_e32 v161, 0xffff0000, v31
	v_lshlrev_b32_e32 v124, 16, v34
	v_and_b32_e32 v125, 0xffff0000, v34
	v_lshlrev_b32_e32 v162, 16, v35
	v_and_b32_e32 v163, 0xffff0000, v35
	v_lshlrev_b32_e32 v126, 16, v38
	v_and_b32_e32 v127, 0xffff0000, v38
	v_lshlrev_b32_e32 v164, 16, v39
	v_and_b32_e32 v165, 0xffff0000, v39
	v_lshlrev_b32_e32 v128, 16, v42
	v_and_b32_e32 v129, 0xffff0000, v42
	v_lshlrev_b32_e32 v166, 16, v43
	v_and_b32_e32 v167, 0xffff0000, v43
	v_lshlrev_b32_e32 v140, 16, v46
	v_and_b32_e32 v141, 0xffff0000, v46
	v_lshlrev_b32_e32 v168, 16, v47
	v_and_b32_e32 v169, 0xffff0000, v47
	v_lshlrev_b32_e32 v142, 16, v50
	v_and_b32_e32 v143, 0xffff0000, v50
	v_lshlrev_b32_e32 v170, 16, v51
	v_and_b32_e32 v171, 0xffff0000, v51
	v_pk_fma_f32 v[144:145], v[54:55], v[122:123], 0 op_sel_hi:[1,1,0]
	v_pk_fma_f32 v[152:153], v[54:55], v[124:125], 0 op_sel_hi:[1,1,0]
	v_pk_fma_f32 v[146:147], v[56:57], v[160:161], 0 op_sel_hi:[1,1,0]
	v_pk_fma_f32 v[154:155], v[56:57], v[162:163], 0 op_sel_hi:[1,1,0]
	v_pk_fma_f32 v[144:145], v[62:63], v[124:125], v[144:145]
	v_pk_fma_f32 v[152:153], v[62:63], v[126:127], v[152:153]
	v_pk_fma_f32 v[146:147], v[64:65], v[162:163], v[146:147]
	v_pk_fma_f32 v[154:155], v[64:65], v[164:165], v[154:155]
	v_pk_fma_f32 v[144:145], v[70:71], v[126:127], v[144:145]
	v_pk_fma_f32 v[152:153], v[70:71], v[128:129], v[152:153]
	v_pk_fma_f32 v[146:147], v[72:73], v[164:165], v[146:147]
	v_pk_fma_f32 v[154:155], v[72:73], v[166:167], v[154:155]
	v_pk_fma_f32 v[144:145], v[106:107], v[128:129], v[144:145]
	v_pk_fma_f32 v[152:153], v[106:107], v[140:141], v[152:153]
	v_pk_fma_f32 v[146:147], v[108:109], v[166:167], v[146:147]
	v_pk_fma_f32 v[154:155], v[108:109], v[168:169], v[154:155]
	v_pk_fma_f32 v[144:145], v[114:115], v[140:141], v[144:145]
	v_pk_fma_f32 v[152:153], v[114:115], v[142:143], v[152:153]
	v_pk_fma_f32 v[146:147], v[116:117], v[168:169], v[146:147]
	v_pk_fma_f32 v[154:155], v[116:117], v[170:171], v[154:155]
	v_lshlrev_b32_e32 v122, 16, v32
	v_and_b32_e32 v123, 0xffff0000, v32
	v_lshlrev_b32_e32 v160, 16, v33
	v_and_b32_e32 v161, 0xffff0000, v33
	v_lshlrev_b32_e32 v124, 16, v36
	v_and_b32_e32 v125, 0xffff0000, v36
	v_lshlrev_b32_e32 v162, 16, v37
	v_and_b32_e32 v163, 0xffff0000, v37
	v_lshlrev_b32_e32 v126, 16, v40
	v_and_b32_e32 v127, 0xffff0000, v40
	v_lshlrev_b32_e32 v164, 16, v41
	v_and_b32_e32 v165, 0xffff0000, v41
	v_lshlrev_b32_e32 v128, 16, v44
	v_and_b32_e32 v129, 0xffff0000, v44
	v_lshlrev_b32_e32 v166, 16, v45
	v_and_b32_e32 v167, 0xffff0000, v45
	v_lshlrev_b32_e32 v140, 16, v48
	v_and_b32_e32 v141, 0xffff0000, v48
	v_lshlrev_b32_e32 v168, 16, v49
	v_and_b32_e32 v169, 0xffff0000, v49
	v_lshlrev_b32_e32 v142, 16, v52
	v_and_b32_e32 v143, 0xffff0000, v52
	v_lshlrev_b32_e32 v170, 16, v53
	v_and_b32_e32 v171, 0xffff0000, v53
	v_pk_fma_f32 v[148:149], v[58:59], v[122:123], 0 op_sel_hi:[1,1,0]
	v_pk_fma_f32 v[156:157], v[58:59], v[124:125], 0 op_sel_hi:[1,1,0]
	v_pk_fma_f32 v[150:151], v[60:61], v[160:161], 0 op_sel_hi:[1,1,0]
	v_pk_fma_f32 v[158:159], v[60:61], v[162:163], 0 op_sel_hi:[1,1,0]
	v_pk_fma_f32 v[148:149], v[66:67], v[124:125], v[148:149]
	v_pk_fma_f32 v[156:157], v[66:67], v[126:127], v[156:157]
	v_pk_fma_f32 v[150:151], v[68:69], v[162:163], v[150:151]
	v_pk_fma_f32 v[158:159], v[68:69], v[164:165], v[158:159]
	v_pk_fma_f32 v[148:149], v[74:75], v[126:127], v[148:149]
	v_pk_fma_f32 v[156:157], v[74:75], v[128:129], v[156:157]
	v_pk_fma_f32 v[150:151], v[76:77], v[164:165], v[150:151]
	v_pk_fma_f32 v[158:159], v[76:77], v[166:167], v[158:159]
	v_pk_fma_f32 v[148:149], v[110:111], v[128:129], v[148:149]
	v_pk_fma_f32 v[156:157], v[110:111], v[140:141], v[156:157]
	v_pk_fma_f32 v[150:151], v[112:113], v[166:167], v[150:151]
	v_pk_fma_f32 v[158:159], v[112:113], v[168:169], v[158:159]
	v_pk_fma_f32 v[148:149], v[118:119], v[140:141], v[148:149]
	v_pk_fma_f32 v[156:157], v[118:119], v[142:143], v[156:157]
	v_pk_fma_f32 v[150:151], v[120:121], v[168:169], v[150:151]
	v_pk_fma_f32 v[158:159], v[120:121], v[170:171], v[158:159]
	v_pk_mul_f32 v[160:161], v[144:145], v[176:177] op_sel_hi:[1,0]
	v_pk_mul_f32 v[162:163], v[146:147], v[176:177] op_sel_hi:[1,0]
	v_pk_mul_f32 v[164:165], v[148:149], v[176:177] op_sel_hi:[1,0]
	v_pk_mul_f32 v[166:167], v[150:151], v[176:177] op_sel_hi:[1,0]
	v_pk_mul_f32 v[168:169], v[152:153], v[176:177] op_sel_hi:[1,0]
	v_pk_mul_f32 v[170:171], v[154:155], v[176:177] op_sel_hi:[1,0]
	v_pk_mul_f32 v[172:173], v[156:157], v[176:177] op_sel_hi:[1,0]
	v_pk_mul_f32 v[174:175], v[158:159], v[176:177] op_sel_hi:[1,0]
	v_exp_f32_e32 v160, v160
	v_exp_f32_e32 v161, v161
	v_exp_f32_e32 v162, v162
	v_exp_f32_e32 v163, v163
	v_exp_f32_e32 v164, v164
	v_exp_f32_e32 v165, v165
	v_exp_f32_e32 v166, v166
	v_exp_f32_e32 v167, v167
	v_exp_f32_e32 v168, v168
	v_exp_f32_e32 v169, v169
	v_exp_f32_e32 v170, v170
; __device__ void dn_item(const Params& p, int l, int item, char* smem, int wv) {
;     ...
;         float ss = 0.f;
; #pragma unroll
;         for (int e = 0; e < 16; ++e) { acc[e] = siluf_(acc[e]); ss += acc[e] * acc[e]; }
;         float sc = 1.f;
;         if (part < 2) {
;           ss += shx(ss, 1, lane);
;           ss += shx(ss, 2, lane);
;           sc = rsqrtf(ss + 1e-6f) * (part == 0 ? 0.125f : 1.f);
;         }
; #pragma unroll
;         for (int e = 0; e < 16; ++e) acc[e] *= sc;
;         u16* dst = (part == 0 ? Qb : (part == 1 ? Kb : Vb)) + ip * 72 + dc * 16;
;         *(uint4*)dst = make_uint4(pack2(acc[0], acc[1]), pack2(acc[2], acc[3]), pack2(acc[4], acc[5]), pack2(acc[6], acc[7]));
;         *(uint4*)(dst + 8) = make_uint4(pack2(acc[8], acc[9]), pack2(acc[10], acc[11]), pack2(acc[12], acc[13]), pack2(acc[14], acc[15]));
;     ...
;     lds_barrier();
;     if (step + 1 < 68) prefetch(step + 1);
;     f32x4 rhs[4];
;     {
;       const int i0 = 16 * wave + fq * 4;
;       bf16x8 ka[2], qa[2], kbt[2][4];
;       float gi[4], bi[4], gj[4];
;       u16 vraw[4][4];
; #pragma unroll
;       for (int kk = 0; kk < 2; ++kk) {
;         ka[kk] = *(const bf16x8*)(Kb + (16 * wave + fr) * 72 + kk * 32 + fq * 8);
;         qa[kk] = *(const bf16x8*)(Qb + (16 * wave + fr) * 72 + kk * 32 + fq * 8);
; #pragma unroll
;         for (int n = 0; n < 4; ++n) kbt[kk][n] = *(const bf16x8*)(Kb + (n * 16 + fr) * 72 + kk * 32 + fq * 8);
;       }
;       __builtin_amdgcn_sched_barrier(0);
;       f32x4 kk4[4], qk[4];
; #pragma unroll
;       for (int n = 0; n < 4; ++n) {
;         kk4[n] = (f32x4){0.f, 0.f, 0.f, 0.f};
;         qk[n] = (f32x4){0.f, 0.f, 0.f, 0.f};
;         rhs[n] = (f32x4){0.f, 0.f, 0.f, 0.f};
;       }
; #pragma unroll
;       for (int kk = 0; kk < 2; ++kk)
; #pragma unroll
;         for (int n = 0; n < 4; ++n) {
;           kk4[n] = mfma16(ka[kk], kbt[kk][n], kk4[n]);
;           qk[n] = mfma16(qa[kk], kbt[kk][n], qk[n]);
;         }
;       __builtin_amdgcn_sched_barrier(0);
;       {
;         bf16x8 sbt[2][4];
; #pragma unroll
;         for (int kk = 0; kk < 2; ++kk)
; #pragma unroll
;           for (int n = 0; n < 4; ++n) sbt[kk][n] = *(const bf16x8*)(Stb + (n * 16 + fr) * 72 + kk * 32 + fq * 8);
; #pragma unroll
;         for (int j = 0; j < 4; ++j) { gi[j] = gcs[i0 + j]; bi[j] = bts[i0 + j]; gj[j] = gcs[j * 16 + fr]; }
; #pragma unroll
	v_exp_f32_e32 v171, v171
	v_exp_f32_e32 v172, v172
	v_exp_f32_e32 v173, v173
	v_exp_f32_e32 v174, v174
	v_exp_f32_e32 v175, v175
	v_pk_add_f32 v[160:161], v[160:161], v[180:181] op_sel_hi:[1,0]
	v_pk_add_f32 v[162:163], v[162:163], v[180:181] op_sel_hi:[1,0]
	v_pk_add_f32 v[164:165], v[164:165], v[180:181] op_sel_hi:[1,0]
	v_pk_add_f32 v[166:167], v[166:167], v[180:181] op_sel_hi:[1,0]
	v_pk_add_f32 v[168:169], v[168:169], v[180:181] op_sel_hi:[1,0]
	v_pk_add_f32 v[170:171], v[170:171], v[180:181] op_sel_hi:[1,0]
	v_pk_add_f32 v[172:173], v[172:173], v[180:181] op_sel_hi:[1,0]
	v_pk_add_f32 v[174:175], v[174:175], v[180:181] op_sel_hi:[1,0]
	v_rcp_f32_e32 v160, v160
	v_rcp_f32_e32 v161, v161
	v_rcp_f32_e32 v162, v162
	v_rcp_f32_e32 v163, v163
	v_rcp_f32_e32 v164, v164
	v_rcp_f32_e32 v165, v165
	v_rcp_f32_e32 v166, v166
	v_rcp_f32_e32 v167, v167
	v_rcp_f32_e32 v168, v168
	v_rcp_f32_e32 v169, v169
	v_rcp_f32_e32 v170, v170
	v_rcp_f32_e32 v171, v171
	v_rcp_f32_e32 v172, v172
	v_rcp_f32_e32 v173, v173
	v_rcp_f32_e32 v174, v174
	v_rcp_f32_e32 v175, v175
	s_nop 0
	v_pk_mul_f32 v[144:145], v[144:145], v[160:161]
	v_pk_mul_f32 v[146:147], v[146:147], v[162:163]
	v_pk_mul_f32 v[148:149], v[148:149], v[164:165]
	v_pk_mul_f32 v[150:151], v[150:151], v[166:167]
	v_pk_mul_f32 v[152:153], v[152:153], v[168:169]
	v_pk_mul_f32 v[154:155], v[154:155], v[170:171]
	v_pk_mul_f32 v[156:157], v[156:157], v[172:173]
	v_pk_mul_f32 v[158:159], v[158:159], v[174:175]
	v_cvt_pk_bf16_f32 v172, v144, v145
	v_cvt_pk_bf16_f32 v173, v146, v147
	v_cvt_pk_bf16_f32 v174, v148, v149
	v_cvt_pk_bf16_f32 v175, v150, v151
	ds_write_b128 v195, v[172:175] offset:36416
	v_cvt_pk_bf16_f32 v136, v152, v153
	v_cvt_pk_bf16_f32 v137, v154, v155
	v_cvt_pk_bf16_f32 v138, v156, v157
	v_cvt_pk_bf16_f32 v139, v158, v159
	ds_write_b128 v196, v[136:139] offset:36416
	s_cmp_lg_u32 s42, 63
	s_cselect_b64 s[38:39], -1, 0
	s_cmp_eq_u32 s42, 63
	s_waitcnt lgkmcnt(0)
	s_barrier
.LBB0_357:
	v_add_u32_e32 v0, v80, v87
	ds_read_b128 v[50:53], v82 offset:27200
	ds_read_b128 v[64:67], v82 offset:27264
	ds_read_b128 v[30:33], v82 offset:45632
	ds_read_b128 v[58:61], v82 offset:45696
	ds_read_b128 v[34:37], v0 offset:27200
	ds_read_b128 v[38:41], v0 offset:27264
	ds_read_b128 v[42:45], v0 offset:29504
	ds_read_b128 v[46:49], v0 offset:29568
	ds_read_b128 v[54:57], v0 offset:31808
	ds_read_b128 v[68:71], v0 offset:31872
	ds_read_b128 v[72:75], v0 offset:34112
	ds_read_b128 v[106:109], v0 offset:34176
	s_waitcnt lgkmcnt(7)
	v_mfma_f32_16x16x32_bf16 v[110:113], v[50:53], v[34:37], 0
	v_mfma_f32_16x16x32_bf16 v[34:37], v[30:33], v[34:37], 0
	s_waitcnt lgkmcnt(5)
	v_mfma_f32_16x16x32_bf16 v[114:117], v[50:53], v[42:45], 0
	v_mfma_f32_16x16x32_bf16 v[42:45], v[30:33], v[42:45], 0
	s_waitcnt lgkmcnt(3)
	v_mfma_f32_16x16x32_bf16 v[118:121], v[50:53], v[54:57], 0
	v_mfma_f32_16x16x32_bf16 v[122:125], v[30:33], v[54:57], 0
	s_waitcnt lgkmcnt(1)
	v_mfma_f32_16x16x32_bf16 v[126:129], v[50:53], v[72:75], 0
	v_mfma_f32_16x16x32_bf16 v[30:33], v[30:33], v[72:75], 0
	v_mfma_f32_16x16x32_bf16 v[72:75], v[64:67], v[38:41], v[110:113]
	v_mfma_f32_16x16x32_bf16 v[110:113], v[58:61], v[38:41], v[34:37]
	v_mfma_f32_16x16x32_bf16 v[54:57], v[64:67], v[46:49], v[114:117]
	v_mfma_f32_16x16x32_bf16 v[46:49], v[58:61], v[46:49], v[42:45]
	v_mfma_f32_16x16x32_bf16 v[42:45], v[64:67], v[68:71], v[118:121]
	v_mfma_f32_16x16x32_bf16 v[38:41], v[58:61], v[68:71], v[122:125]
	s_waitcnt lgkmcnt(0)
	v_mfma_f32_16x16x32_bf16 v[34:37], v[64:67], v[106:109], v[126:129]
	v_mfma_f32_16x16x32_bf16 v[30:33], v[58:61], v[106:109], v[30:33]
	v_add_u32_e32 v62, v83, v87
	ds_read_b128 v[58:61], v62 offset:64064
	ds_read_b128 v[68:71], v62 offset:64128
	v_add_u32_e32 v63, v83, v89
	v_add_u32_e32 v62, v83, v203
	ds_read_b128 v[106:109], v63 offset:64064
	ds_read_b128 v[114:117], v63 offset:64128
	ds_read_b128 v[118:121], v62 offset:64064
	ds_read_b128 v[122:125], v62 offset:64128
	v_add_u32_e32 v63, v83, v204
	s_waitcnt lgkmcnt(5)
	v_mfma_f32_16x16x32_bf16 v[58:61], v[50:53], v[58:61], 0
	ds_read_b128 v[126:129], v63 offset:64064
	ds_read_b128 v[132:135], v63 offset:64128
	v_add_u32_e32 v250, v190, v214
	v_readlane_b32 s6, v254, 48
	s_waitcnt lgkmcnt(5)
	v_mfma_f32_16x16x32_bf16 v[106:109], v[50:53], v[106:109], 0
	v_readlane_b32 s7, v254, 49
	v_add_u32_e32 v249, v190, v215
	v_add_u32_e32 v248, v190, v216
	s_waitcnt lgkmcnt(3)
	v_mfma_f32_16x16x32_bf16 v[118:121], v[50:53], v[118:121], 0
	s_waitcnt lgkmcnt(1)
	v_mfma_f32_16x16x32_bf16 v[50:53], v[50:53], v[126:129], 0
	v_mfma_f32_16x16x32_bf16 v[68:71], v[64:67], v[68:71], v[58:61]
	s_nop 2
	ds_read_b64 v[60:61], v205
	ds_read_b64 v[58:59], v206
	ds_read_b32 v76, v207
	ds_read_b32 v77, v208
	ds_read_b32 v126, v210
	ds_read_b32 v127, v212
	ds_read_b32 v128, v213
	ds_read_b64 v[62:63], v211
	ds_read_b32 v129, v209
	v_mfma_f32_16x16x32_bf16 v[106:109], v[64:67], v[114:117], v[106:109]
	v_mfma_f32_16x16x32_bf16 v[114:117], v[64:67], v[122:125], v[118:121]
	s_waitcnt lgkmcnt(9)
	v_mfma_f32_16x16x32_bf16 v[50:53], v[64:67], v[132:135], v[50:53]
	s_waitcnt lgkmcnt(6)
	v_sub_f32_e32 v65, v60, v76
	v_mul_f32_e32 v65, 0x3fb8aa3b, v65
	v_mul_f32_e32 v64, 0x3fb8aa3b, v60
	v_exp_f32_e32 v65, v65
	v_exp_f32_e32 v118, v64
	v_mul_f32_e32 v64, 0x3fb8aa3b, v61
	v_exp_f32_e32 v119, v64
	s_waitcnt lgkmcnt(4)
	v_mul_f32_e32 v64, 0x3fb8aa3b, v126
	v_exp_f32_e32 v120, v64
	s_waitcnt lgkmcnt(3)
; __device__ __forceinline__ u16 f2bf(float f) { return (u16)(pack2(f, 0.f) & 0xffffu); }
; __device__ __forceinline__ float bf2f(u16 h) { return __uint_as_float(((unsigned)h) << 16); }
; __device__ void dn_item(const Params& p, int l, int item, char* smem, int wv) {
;     ...
;       float eg[4];
; #pragma unroll
;       for (int j = 0; j < 4; ++j) eg[j] = __expf(gi[j]);
; #pragma unroll
;       for (int n = 0; n < 4; ++n) {
;         const int jj = n * 16 + fr;
;         float lv[4];
; #pragma unroll
;         for (int j = 0; j < 4; ++j) {
;           int i = i0 + j;
;           float e = (i >= jj) ? __expf(gi[j] - gj[n]) : 0.f;
;           lv[j] = (i > jj) ? bi[j] * kk4[n][j] * e : 0.f;
;           Ib[i * 72 + jj] = f2bf(qk[n][j] * e);
;           rhs[n][j] = bi[j] * (bf2f(vraw[n][j]) - eg[j] * rhs[n][j]);
;         }
;         *(float4*)(LfT + jj * 68 + i0) = make_float4(lv[0], lv[1], lv[2], lv[3]);
;       }
	v_mul_f32_e32 v64, 0x3fb8aa3b, v127
	v_exp_f32_e32 v121, v64
	v_cndmask_b32_e64 v65, v65, 0, s[50:51]
	v_mul_f32_e32 v64, v72, v58
	v_mul_f32_e32 v64, v64, v65
	v_mul_f32_e32 v65, v110, v65
	v_cvt_pk_bf16_f32 v66, v65, s0
	v_sub_f32_e32 v65, v61, v76
	v_mul_f32_e32 v65, 0x3fb8aa3b, v65
	v_exp_f32_e32 v65, v65
	ds_read_u16 v67, v250 offset:36416
	ds_read_u16 v72, v250 offset:36448
	ds_read_u16 v110, v250 offset:36560
	ds_read_u16 v122, v250 offset:36592
	ds_read_u16 v123, v250 offset:36480
	ds_read_u16 v124, v250 offset:36624
	ds_read_u16 v125, v250 offset:36656
	ds_read_u16 v132, v250 offset:36512
	s_waitcnt lgkmcnt(7)
	v_lshlrev_b32_e32 v67, 16, v67
	v_cndmask_b32_e64 v64, 0, v64, s[6:7]
	v_fma_f32 v67, -v118, v68, v67
	v_readlane_b32 s6, v254, 50
	s_waitcnt lgkmcnt(5)
	v_lshlrev_b32_e32 v68, 16, v110
	v_readlane_b32 s7, v254, 51
	v_fma_f32 v68, -v119, v69, v68
	v_mul_f32_e32 v133, v58, v67
	v_cndmask_b32_e64 v67, v65, 0, s[6:7]
	v_mul_f32_e32 v65, v73, v59
	v_mul_f32_e32 v73, v59, v68
	v_sub_f32_e32 v68, v126, v76
	v_sub_f32_e32 v76, v127, v76
	v_mul_f32_e32 v68, 0x3fb8aa3b, v68
	v_mul_f32_e32 v76, 0x3fb8aa3b, v76
	v_mul_f32_e32 v65, v65, v67
	v_mul_f32_e32 v67, v111, v67
	v_exp_f32_e32 v68, v68
	ds_read_u16 v69, v249 offset:36416
	ds_read_u16 v110, v249 offset:36448
	ds_read_u16 v111, v248 offset:36416
	ds_read_u16 v134, v248 offset:36448
	ds_read_u16 v135, v249 offset:36480
	ds_read_u16 v136, v248 offset:36480
	ds_read_u16 v137, v248 offset:36512
	ds_read_u16 v138, v249 offset:36512
	v_exp_f32_e32 v76, v76
	s_waitcnt lgkmcnt(7)
	v_lshlrev_b32_e32 v69, 16, v69
	v_fma_f32 v70, -v120, v70, v69
	s_waitcnt lgkmcnt(5)
	v_lshlrev_b32_e32 v69, 16, v111
	v_cndmask_b32_e64 v65, v65, 0, s[50:51]
	v_cvt_pk_bf16_f32 v67, v67, s0
	v_fma_f32 v71, -v121, v71, v69
	v_readlane_b32 s6, v254, 52
	v_readlane_b32 s7, v254, 53
	v_add_u32_e32 v111, v217, v214
	ds_write_b16 v111, v66 offset:17408
	ds_write_b16 v111, v67 offset:17552
	v_cndmask_b32_e64 v69, v76, 0, s[6:7]
	v_readlane_b32 s6, v254, 54
	v_readlane_b32 s7, v254, 55
	v_add_u32_e32 v76, v217, v215
	v_mul_f32_e32 v54, v54, v58
	v_cndmask_b32_e64 v68, v68, 0, s[6:7]
	v_mul_f32_e32 v66, v112, v68
	v_cvt_pk_bf16_f32 v66, v66, s0
	ds_write_b16 v76, v66 offset:17408
	v_pk_mul_f32 v[66:67], v[74:75], v[62:63]
	v_sub_f32_e32 v74, v60, v77
	v_readlane_b32 s6, v254, 56
	v_mul_f32_e32 v74, 0x3fb8aa3b, v74
	v_pk_mul_f32 v[66:67], v[66:67], v[68:69]
	v_readlane_b32 s7, v254, 57
	v_exp_f32_e32 v74, v74
	v_mul_f32_e32 v68, v113, v69
	v_cndmask_b32_e64 v67, 0, v67, s[6:7]
	v_readlane_b32 s6, v254, 58
	v_readlane_b32 s7, v254, 59
	v_cvt_pk_bf16_f32 v68, v68, s0
	v_add_u32_e32 v69, v217, v216
	v_cndmask_b32_e64 v66, 0, v66, s[6:7]
	ds_write_b16 v69, v68 offset:17408
	ds_write_b128 v240, v[64:67]
	v_cndmask_b32_e64 v64, v74, 0, s[64:65]
	v_mul_f32_e32 v46, v46, v64
	v_cvt_pk_bf16_f32 v46, v46, s0
	ds_write_b16 v111, v46 offset:17440
	v_sub_f32_e32 v46, v61, v77
	v_mul_f32_e32 v46, 0x3fb8aa3b, v46
	v_readlane_b32 s6, v254, 60
	v_exp_f32_e32 v46, v46
	v_mul_f32_e32 v54, v54, v64
	v_readlane_b32 s7, v254, 61
	v_mul_f32_e32 v55, v55, v59
	v_pk_mul_f32 v[56:57], v[56:57], v[62:63]
	v_cndmask_b32_e64 v54, 0, v54, s[6:7]
	v_readlane_b32 s6, v254, 62
	v_readlane_b32 s7, v254, 63
	v_mul_f32_e32 v43, v43, v59
	v_pk_mul_f32 v[44:45], v[44:45], v[62:63]
	v_cndmask_b32_e64 v46, v46, 0, s[6:7]
	v_mul_f32_e32 v55, v55, v46
	v_mul_f32_e32 v46, v47, v46
	v_lshlrev_b32_e32 v47, 16, v110
	v_cvt_pk_bf16_f32 v46, v46, s0
	v_fma_f32 v47, -v120, v108, v47
	ds_write_b16 v111, v46 offset:17584
	v_lshlrev_b32_e32 v46, 16, v122
	v_mul_f32_e32 v66, v62, v47
	v_sub_f32_e32 v47, v127, v77
	v_fma_f32 v46, -v119, v107, v46
	v_mul_f32_e32 v47, 0x3fb8aa3b, v47
	v_mul_f32_e32 v65, v59, v46
	v_sub_f32_e32 v46, v126, v77
	v_exp_f32_e32 v47, v47
	v_mul_f32_e32 v46, 0x3fb8aa3b, v46
	v_exp_f32_e32 v46, v46
	v_readlane_b32 s6, v255, 0
	v_readlane_b32 s7, v255, 1
	v_cndmask_b32_e64 v55, v55, 0, s[64:65]
	v_mul_f32_e32 v42, v42, v58
	v_cndmask_b32_e64 v47, v47, 0, s[6:7]
	v_readlane_b32 s6, v255, 2
	v_readlane_b32 s7, v255, 3
	v_mul_f32_e32 v35, v35, v59
	v_pk_mul_f32 v[36:37], v[36:37], v[62:63]
	v_cndmask_b32_e64 v46, v46, 0, s[6:7]
	v_mul_f32_e32 v48, v48, v46
	v_pk_mul_f32 v[56:57], v[56:57], v[46:47]
	v_mul_f32_e32 v46, v49, v47
	v_sub_f32_e32 v47, v60, v129
	v_mul_f32_e32 v47, 0x3fb8aa3b, v47
	v_readlane_b32 s6, v255, 4
	v_exp_f32_e32 v47, v47
	v_readlane_b32 s7, v255, 5
	v_cvt_pk_bf16_f32 v48, v48, s0
	v_cvt_pk_bf16_f32 v46, v46, s0
	v_cndmask_b32_e64 v57, 0, v57, s[6:7]
	v_readlane_b32 s6, v255, 6
	v_readlane_b32 s7, v255, 7
	ds_write_b16 v76, v48 offset:17440
	v_mul_f32_e32 v34, v34, v58
	v_cndmask_b32_e64 v56, 0, v56, s[6:7]
	ds_write_b16 v69, v46 offset:17440
	ds_write_b128 v240, v[54:57] offset:4352
	v_cndmask_b32_e64 v46, v47, 0, s[78:79]
	v_mul_f32_e32 v38, v38, v46
	v_cvt_pk_bf16_f32 v38, v38, s0
	ds_write_b16 v111, v38 offset:17472
	v_sub_f32_e32 v38, v61, v129
	v_mul_f32_e32 v38, 0x3fb8aa3b, v38
	v_exp_f32_e32 v38, v38
	v_mul_f32_e32 v42, v42, v46
	v_cndmask_b32_e64 v42, 0, v42, s[80:81]
	v_lshlrev_b32_e32 v64, 16, v72
	v_cndmask_b32_e64 v38, v38, 0, s[82:83]
	v_mul_f32_e32 v43, v43, v38
	v_mul_f32_e32 v38, v39, v38
	v_cvt_pk_bf16_f32 v38, v38, s0
	ds_write_b16 v111, v38 offset:17616
	v_lshlrev_b32_e32 v38, 16, v124
	s_waitcnt lgkmcnt(14)
; __device__ __forceinline__ u16 f2bf(float f) { return (u16)(pack2(f, 0.f) & 0xffffu); }
; __device__ __forceinline__ float bf2f(u16 h) { return __uint_as_float(((unsigned)h) << 16); }
; __device__ void dn_item(const Params& p, int l, int item, char* smem, int wv) {
;     ...
;         for (int j = 0; j < 4; ++j) {
;           int i = i0 + j;
;           float e = (i >= jj) ? __expf(gi[j] - gj[n]) : 0.f;
;           lv[j] = (i > jj) ? bi[j] * kk4[n][j] * e : 0.f;
;           Ib[i * 72 + jj] = f2bf(qk[n][j] * e);
;           rhs[n][j] = bi[j] * (bf2f(vraw[n][j]) - eg[j] * rhs[n][j]);
;         }
;         *(float4*)(LfT + jj * 68 + i0) = make_float4(lv[0], lv[1], lv[2], lv[3]);
;       }
;     }
;     lds_barrier();
; #pragma unroll
;     for (int n = 0; n < 4; ++n)
; #pragma unroll
;       for (int j = 0; j < 4; ++j) X[(16 * wave + fq * 4 + j) * XS + n * 16 + fr] = rhs[n][j];
;     {
;       const int c = lane & 15;
;       const float* ld = LfT + (16 * wave) * 68 + 16 * wave;
;       float x[16];
; #pragma unroll
;       for (int i = 0; i < 16; ++i) x[i] = (i == c) ? 1.f : 0.f;
; #pragma unroll
;       for (int hb = 0; hb < 2; ++hb) {
;         const int j0 = hb ? 7 : 0, j1 = hb ? 15 : 7;
;         float4 lr[8][4];
; #pragma unroll
;         for (int jq = 0; jq < 8; ++jq) {
;           const int j = j0 + jq;
;           if (j < j1) {
; #pragma unroll
;             for (int q4 = 0; q4 < 4; ++q4)
;               if (q4 * 4 + 3 > j) lr[jq][q4] = *(const float4*)(ld + j * 68 + q4 * 4);
;           }
;         }
	v_lshlrev_b32_e32 v39, 16, v135
	v_fma_f32 v38, -v119, v115, v38
	v_fma_f32 v39, -v120, v116, v39
	v_mul_f32_e32 v47, v59, v38
	v_sub_f32_e32 v38, v126, v129
	v_mul_f32_e32 v48, v62, v39
	v_sub_f32_e32 v39, v127, v129
	v_mul_f32_e32 v38, 0x3fb8aa3b, v38
	v_mul_f32_e32 v39, 0x3fb8aa3b, v39
	v_exp_f32_e32 v38, v38
	v_exp_f32_e32 v39, v39
	v_cndmask_b32_e64 v43, v43, 0, s[78:79]
	v_lshlrev_b32_e32 v67, 16, v134
	v_cndmask_b32_e64 v38, v38, 0, s[86:87]
	v_cndmask_b32_e64 v39, v39, 0, s[84:85]
	v_mul_f32_e32 v40, v40, v38
	v_pk_mul_f32 v[44:45], v[44:45], v[38:39]
	v_mul_f32_e32 v38, v41, v39
	v_sub_f32_e32 v39, v60, v128
	v_mul_f32_e32 v39, 0x3fb8aa3b, v39
	v_exp_f32_e32 v39, v39
	v_cvt_pk_bf16_f32 v40, v40, s0
	v_cvt_pk_bf16_f32 v38, v38, s0
	ds_write_b16 v76, v40 offset:17472
	v_cndmask_b32_e64 v45, 0, v45, s[88:89]
	v_cndmask_b32_e64 v44, 0, v44, s[90:91]
	ds_write_b16 v69, v38 offset:17472
	ds_write_b128 v240, v[42:45] offset:8704
	v_cndmask_b32_e64 v38, v39, 0, s[92:93]
	v_mul_f32_e32 v30, v30, v38
	v_cvt_pk_bf16_f32 v30, v30, s0
	ds_write_b16 v111, v30 offset:17504
	v_sub_f32_e32 v30, v61, v128
	v_mul_f32_e32 v30, 0x3fb8aa3b, v30
	v_exp_f32_e32 v30, v30
	v_lshlrev_b32_e32 v46, 16, v123
	v_lshlrev_b32_e32 v49, 16, v136
	v_mul_f32_e32 v34, v34, v38
	v_cndmask_b32_e64 v30, v30, 0, s[96:97]
	v_mul_f32_e32 v35, v35, v30
	v_mul_f32_e32 v30, v31, v30
	v_cvt_pk_bf16_f32 v30, v30, s0
	ds_write_b16 v111, v30 offset:17648
	v_lshlrev_b32_e32 v30, 16, v125
	s_waitcnt lgkmcnt(14)
	v_lshlrev_b32_e32 v31, 16, v138
	v_fma_f32 v30, -v119, v51, v30
	v_fma_f32 v31, -v120, v52, v31
	v_mul_f32_e32 v39, v59, v30
	v_sub_f32_e32 v30, v126, v128
	v_mul_f32_e32 v40, v62, v31
	v_sub_f32_e32 v31, v127, v128
	v_mul_f32_e32 v30, 0x3fb8aa3b, v30
	v_mul_f32_e32 v31, 0x3fb8aa3b, v31
	v_exp_f32_e32 v30, v30
	v_exp_f32_e32 v31, v31
	v_lshlrev_b32_e32 v38, 16, v132
	v_lshlrev_b32_e32 v41, 16, v137
	v_cndmask_b32_e64 v30, v30, 0, s[0:1]
	v_cndmask_b32_e64 v31, v31, 0, s[98:99]
	v_mul_f32_e32 v32, v32, v30
	v_pk_mul_f32 v[36:37], v[36:37], v[30:31]
	v_mul_f32_e32 v30, v33, v31
	v_cvt_pk_bf16_f32 v32, v32, s0
	v_cvt_pk_bf16_f32 v30, v30, s0
	v_fma_f32 v64, -v118, v106, v64
	v_fma_f32 v67, -v121, v109, v67
	v_fma_f32 v46, -v118, v114, v46
	v_fma_f32 v49, -v121, v117, v49
	v_cndmask_b32_e64 v34, 0, v34, s[48:49]
	v_fma_f32 v38, -v118, v50, v38
	v_cndmask_b32_e64 v35, v35, 0, s[92:93]
	v_fma_f32 v41, -v121, v53, v41
	ds_write_b16 v76, v32 offset:17504
	v_cndmask_b32_e64 v37, 0, v37, s[2:3]
	v_cndmask_b32_e64 v36, 0, v36, s[4:5]
	ds_write_b16 v69, v30 offset:17504
	ds_write_b128 v240, v[34:37] offset:13056
	v_mul_f32_e32 v70, v62, v70
	v_mul_f32_e32 v68, v63, v71
	v_mul_f32_e32 v64, v58, v64
	v_mul_f32_e32 v67, v63, v67
	v_mul_f32_e32 v46, v58, v46
	v_mul_f32_e32 v49, v63, v49
	v_mul_f32_e32 v38, v58, v38
	v_mul_f32_e32 v41, v63, v41
	s_waitcnt lgkmcnt(0)
	s_barrier
	ds_write_b32 v241, v133 offset:27200
	ds_write_b32 v241, v73 offset:27472
	ds_write_b32 v242, v70 offset:27200
	ds_write_b32 v243, v68 offset:27200
	ds_write_b32 v241, v64 offset:27264
	ds_write_b32 v241, v65 offset:27536
	ds_write_b32 v242, v66 offset:27264
	ds_write_b32 v243, v67 offset:27264
	ds_write_b32 v241, v46 offset:27328
	ds_write_b32 v241, v47 offset:27600
	ds_write_b32 v242, v48 offset:27328
	ds_write_b32 v243, v49 offset:27328
	ds_write_b32 v241, v38 offset:27392
	ds_write_b32 v241, v39 offset:27664
	ds_write_b32 v242, v40 offset:27392
	ds_write_b32 v243, v41 offset:27392
	ds_read_b32 v180, v191 offset:4
	ds_read_b64 v[30:31], v191 offset:8
	ds_read_b128 v[32:35], v191 offset:16
	ds_read_b128 v[36:39], v191 offset:32
	ds_read_b128 v[40:43], v191 offset:48
	ds_read_b64 v[44:45], v191 offset:280
	ds_read_b128 v[46:49], v191 offset:288
	ds_read_b128 v[50:53], v191 offset:304
	ds_read_b128 v[54:57], v191 offset:320
	ds_read_b32 v179, v191 offset:556
	ds_read_b128 v[58:61], v191 offset:560
	ds_read_b128 v[62:65], v191 offset:576
	ds_read_b128 v[66:69], v191 offset:592
	ds_read_b128 v[70:73], v191 offset:832
	ds_read_b128 v[74:77], v191 offset:848
	ds_read_b128 v[106:109], v191 offset:864
	ds_read_b32 v176, v191 offset:1108
	ds_read_b64 v[110:111], v191 offset:1112
	ds_read_b128 v[112:115], v191 offset:1120
	ds_read_b128 v[116:119], v191 offset:1136
	ds_read_b64 v[120:121], v191 offset:1384
	ds_read_b128 v[122:125], v191 offset:1392
	ds_read_b128 v[126:129], v191 offset:1408
	ds_read_b32 v132, v191 offset:1660
	ds_read_b128 v[134:137], v191 offset:1664
	ds_read_b128 v[138:141], v191 offset:1680
	s_and_saveexec_b64 s[6:7], s[46:47]
	s_cbranch_execz .LBB0_359
; __device__ void dn_item(const Params& p, int l, int item, char* smem, int wv) {
;     ...
;       for (int hb = 0; hb < 2; ++hb) {
;         const int j0 = hb ? 7 : 0, j1 = hb ? 15 : 7;
;         float4 lr[8][4];
; #pragma unroll
;         for (int jq = 0; jq < 8; ++jq) {
;           const int j = j0 + jq;
;           if (j < j1) {
; #pragma unroll
;             for (int q4 = 0; q4 < 4; ++q4)
;               if (q4 * 4 + 3 > j) lr[jq][q4] = *(const float4*)(ld + j * 68 + q4 * 4);
;           }
;         }
;         __builtin_amdgcn_sched_barrier(0);
; #pragma unroll
;         for (int jq = 0; jq < 8; ++jq) {
;           const int j = j0 + jq;
;           if (j < j1) {
;             const float xj = x[j];
; #pragma unroll
;             for (int q4 = 0; q4 < 4; ++q4) {
;               if (q4 * 4 + 3 > j) {
;                 float4 lq = lr[jq][q4];
;                 if (q4 * 4 + 0 > j) x[q4 * 4 + 0] -= lq.x * xj;
;                 if (q4 * 4 + 1 > j) x[q4 * 4 + 1] -= lq.y * xj;
;                 if (q4 * 4 + 2 > j) x[q4 * 4 + 2] -= lq.z * xj;
;                 if (q4 * 4 + 3 > j) x[q4 * 4 + 3] -= lq.w * xj;
;               }
;             }
;           }
;         }
;         __builtin_amdgcn_sched_barrier(0);
;       }
	s_waitcnt lgkmcnt(13)
	v_fma_f32 v161, -v180, v218, v219
	v_pk_fma_f32 v[162:163], v[30:31], v[218:219], v[220:221] op_sel_hi:[1,0,1] neg_lo:[1,0,0] neg_hi:[1,0,0]
	v_pk_fma_f32 v[164:165], v[32:33], v[218:219], v[222:223] op_sel_hi:[1,0,1] neg_lo:[1,0,0] neg_hi:[1,0,0]
	v_pk_fma_f32 v[166:167], v[34:35], v[218:219], v[224:225] op_sel_hi:[1,0,1] neg_lo:[1,0,0] neg_hi:[1,0,0]
	v_pk_fma_f32 v[168:169], v[36:37], v[218:219], v[226:227] op_sel_hi:[1,0,1] neg_lo:[1,0,0] neg_hi:[1,0,0]
	v_pk_fma_f32 v[170:171], v[38:39], v[218:219], v[228:229] op_sel_hi:[1,0,1] neg_lo:[1,0,0] neg_hi:[1,0,0]
	v_pk_fma_f32 v[172:173], v[40:41], v[218:219], v[230:231] op_sel_hi:[1,0,1] neg_lo:[1,0,0] neg_hi:[1,0,0]
	v_pk_fma_f32 v[174:175], v[42:43], v[218:219], v[232:233] op_sel_hi:[1,0,1] neg_lo:[1,0,0] neg_hi:[1,0,0]
	v_pk_fma_f32 v[162:163], v[44:45], v[160:161], v[162:163] op_sel:[0,1,0] op_sel_hi:[1,1,1] neg_lo:[1,0,0] neg_hi:[1,0,0]
	v_pk_fma_f32 v[164:165], v[46:47], v[160:161], v[164:165] op_sel:[0,1,0] op_sel_hi:[1,1,1] neg_lo:[1,0,0] neg_hi:[1,0,0]
	v_pk_fma_f32 v[166:167], v[48:49], v[160:161], v[166:167] op_sel:[0,1,0] op_sel_hi:[1,1,1] neg_lo:[1,0,0] neg_hi:[1,0,0]
	v_pk_fma_f32 v[168:169], v[50:51], v[160:161], v[168:169] op_sel:[0,1,0] op_sel_hi:[1,1,1] neg_lo:[1,0,0] neg_hi:[1,0,0]
	v_pk_fma_f32 v[170:171], v[52:53], v[160:161], v[170:171] op_sel:[0,1,0] op_sel_hi:[1,1,1] neg_lo:[1,0,0] neg_hi:[1,0,0]
	v_pk_fma_f32 v[172:173], v[54:55], v[160:161], v[172:173] op_sel:[0,1,0] op_sel_hi:[1,1,1] neg_lo:[1,0,0] neg_hi:[1,0,0]
	v_pk_fma_f32 v[174:175], v[56:57], v[160:161], v[174:175] op_sel:[0,1,0] op_sel_hi:[1,1,1] neg_lo:[1,0,0] neg_hi:[1,0,0]
	v_fma_f32 v163, -v179, v162, v163
	v_pk_fma_f32 v[164:165], v[58:59], v[162:163], v[164:165] op_sel_hi:[1,0,1] neg_lo:[1,0,0] neg_hi:[1,0,0]
	v_pk_fma_f32 v[166:167], v[60:61], v[162:163], v[166:167] op_sel_hi:[1,0,1] neg_lo:[1,0,0] neg_hi:[1,0,0]
	v_pk_fma_f32 v[168:169], v[62:63], v[162:163], v[168:169] op_sel_hi:[1,0,1] neg_lo:[1,0,0] neg_hi:[1,0,0]
	v_pk_fma_f32 v[170:171], v[64:65], v[162:163], v[170:171] op_sel_hi:[1,0,1] neg_lo:[1,0,0] neg_hi:[1,0,0]
	v_pk_fma_f32 v[172:173], v[66:67], v[162:163], v[172:173] op_sel_hi:[1,0,1] neg_lo:[1,0,0] neg_hi:[1,0,0]
	v_pk_fma_f32 v[174:175], v[68:69], v[162:163], v[174:175] op_sel_hi:[1,0,1] neg_lo:[1,0,0] neg_hi:[1,0,0]
	ds_read_b128 v[54:57], v191 offset:1936
	ds_read_b128 v[50:53], v191 offset:1952
	ds_read_b32 v180, v191 offset:2212
	ds_read_b64 v[44:45], v191 offset:2216
	ds_read_b128 v[46:49], v191 offset:2224
	ds_read_b64 v[30:31], v191 offset:2488
	ds_read_b128 v[40:43], v191 offset:2496
	ds_read_b32 v133, v191 offset:2764
	ds_read_b128 v[36:39], v191 offset:2768
	ds_read_b128 v[32:35], v191 offset:3040
	ds_read_b32 v142, v191 offset:3316
	ds_read_b64 v[144:145], v191 offset:3320
	ds_read_b64 v[146:147], v191 offset:3592
	ds_read_b32 v143, v191 offset:3868
	s_waitcnt lgkmcnt(14)
; __device__ void dn_item(const Params& p, int l, int item, char* smem, int wv) {
;     ...
; #pragma unroll
;         for (int jq = 0; jq < 8; ++jq) {
;           const int j = j0 + jq;
;           if (j < j1) {
;             const float xj = x[j];
; #pragma unroll
;             for (int q4 = 0; q4 < 4; ++q4) {
;               if (q4 * 4 + 3 > j) {
;                 float4 lq = lr[jq][q4];
;                 if (q4 * 4 + 0 > j) x[q4 * 4 + 0] -= lq.x * xj;
;                 if (q4 * 4 + 1 > j) x[q4 * 4 + 1] -= lq.y * xj;
;                 if (q4 * 4 + 2 > j) x[q4 * 4 + 2] -= lq.z * xj;
;                 if (q4 * 4 + 3 > j) x[q4 * 4 + 3] -= lq.w * xj;
;               }
;             }
;           }
;         }
;         __builtin_amdgcn_sched_barrier(0);
;       }
;       if (lane < 16) {
; #pragma unroll
;         for (int i = 0; i < 16; ++i) Tinv[(wave * 16 + i) * 16 + c] = x[i];
;       }
	v_pk_fma_f32 v[164:165], v[70:71], v[162:163], v[164:165] op_sel:[0,1,0] op_sel_hi:[1,1,1] neg_lo:[1,0,0] neg_hi:[1,0,0]
	v_pk_fma_f32 v[166:167], v[72:73], v[162:163], v[166:167] op_sel:[0,1,0] op_sel_hi:[1,1,1] neg_lo:[1,0,0] neg_hi:[1,0,0]
	v_pk_fma_f32 v[168:169], v[74:75], v[162:163], v[168:169] op_sel:[0,1,0] op_sel_hi:[1,1,1] neg_lo:[1,0,0] neg_hi:[1,0,0]
	v_pk_fma_f32 v[170:171], v[76:77], v[162:163], v[170:171] op_sel:[0,1,0] op_sel_hi:[1,1,1] neg_lo:[1,0,0] neg_hi:[1,0,0]
	v_pk_fma_f32 v[172:173], v[106:107], v[162:163], v[172:173] op_sel:[0,1,0] op_sel_hi:[1,1,1] neg_lo:[1,0,0] neg_hi:[1,0,0]
	v_pk_fma_f32 v[174:175], v[108:109], v[162:163], v[174:175] op_sel:[0,1,0] op_sel_hi:[1,1,1] neg_lo:[1,0,0] neg_hi:[1,0,0]
	v_fma_f32 v165, -v176, v164, v165
	v_pk_fma_f32 v[166:167], v[110:111], v[164:165], v[166:167] op_sel_hi:[1,0,1] neg_lo:[1,0,0] neg_hi:[1,0,0]
	v_pk_fma_f32 v[168:169], v[112:113], v[164:165], v[168:169] op_sel_hi:[1,0,1] neg_lo:[1,0,0] neg_hi:[1,0,0]
	v_pk_fma_f32 v[170:171], v[114:115], v[164:165], v[170:171] op_sel_hi:[1,0,1] neg_lo:[1,0,0] neg_hi:[1,0,0]
	v_pk_fma_f32 v[172:173], v[116:117], v[164:165], v[172:173] op_sel_hi:[1,0,1] neg_lo:[1,0,0] neg_hi:[1,0,0]
	v_pk_fma_f32 v[174:175], v[118:119], v[164:165], v[174:175] op_sel_hi:[1,0,1] neg_lo:[1,0,0] neg_hi:[1,0,0]
	v_pk_fma_f32 v[166:167], v[120:121], v[164:165], v[166:167] op_sel:[0,1,0] op_sel_hi:[1,1,1] neg_lo:[1,0,0] neg_hi:[1,0,0]
	v_pk_fma_f32 v[168:169], v[122:123], v[164:165], v[168:169] op_sel:[0,1,0] op_sel_hi:[1,1,1] neg_lo:[1,0,0] neg_hi:[1,0,0]
	v_pk_fma_f32 v[170:171], v[124:125], v[164:165], v[170:171] op_sel:[0,1,0] op_sel_hi:[1,1,1] neg_lo:[1,0,0] neg_hi:[1,0,0]
	v_pk_fma_f32 v[172:173], v[126:127], v[164:165], v[172:173] op_sel:[0,1,0] op_sel_hi:[1,1,1] neg_lo:[1,0,0] neg_hi:[1,0,0]
	v_pk_fma_f32 v[174:175], v[128:129], v[164:165], v[174:175] op_sel:[0,1,0] op_sel_hi:[1,1,1] neg_lo:[1,0,0] neg_hi:[1,0,0]
	v_fma_f32 v167, -v132, v166, v167
	v_pk_fma_f32 v[168:169], v[134:135], v[166:167], v[168:169] op_sel_hi:[1,0,1] neg_lo:[1,0,0] neg_hi:[1,0,0]
	v_pk_fma_f32 v[170:171], v[136:137], v[166:167], v[170:171] op_sel_hi:[1,0,1] neg_lo:[1,0,0] neg_hi:[1,0,0]
	v_pk_fma_f32 v[172:173], v[138:139], v[166:167], v[172:173] op_sel_hi:[1,0,1] neg_lo:[1,0,0] neg_hi:[1,0,0]
	v_pk_fma_f32 v[174:175], v[140:141], v[166:167], v[174:175] op_sel_hi:[1,0,1] neg_lo:[1,0,0] neg_hi:[1,0,0]
	s_waitcnt lgkmcnt(0)
	v_pk_fma_f32 v[168:169], v[54:55], v[166:167], v[168:169] op_sel:[0,1,0] op_sel_hi:[1,1,1] neg_lo:[1,0,0] neg_hi:[1,0,0]
	v_pk_fma_f32 v[170:171], v[56:57], v[166:167], v[170:171] op_sel:[0,1,0] op_sel_hi:[1,1,1] neg_lo:[1,0,0] neg_hi:[1,0,0]
	v_pk_fma_f32 v[172:173], v[50:51], v[166:167], v[172:173] op_sel:[0,1,0] op_sel_hi:[1,1,1] neg_lo:[1,0,0] neg_hi:[1,0,0]
	v_pk_fma_f32 v[174:175], v[52:53], v[166:167], v[174:175] op_sel:[0,1,0] op_sel_hi:[1,1,1] neg_lo:[1,0,0] neg_hi:[1,0,0]
	v_fma_f32 v169, -v180, v168, v169
	v_pk_fma_f32 v[170:171], v[44:45], v[168:169], v[170:171] op_sel_hi:[1,0,1] neg_lo:[1,0,0] neg_hi:[1,0,0]
	v_pk_fma_f32 v[172:173], v[46:47], v[168:169], v[172:173] op_sel_hi:[1,0,1] neg_lo:[1,0,0] neg_hi:[1,0,0]
	v_pk_fma_f32 v[174:175], v[48:49], v[168:169], v[174:175] op_sel_hi:[1,0,1] neg_lo:[1,0,0] neg_hi:[1,0,0]
	v_pk_fma_f32 v[170:171], v[30:31], v[168:169], v[170:171] op_sel:[0,1,0] op_sel_hi:[1,1,1] neg_lo:[1,0,0] neg_hi:[1,0,0]
	v_pk_fma_f32 v[172:173], v[40:41], v[168:169], v[172:173] op_sel:[0,1,0] op_sel_hi:[1,1,1] neg_lo:[1,0,0] neg_hi:[1,0,0]
	v_pk_fma_f32 v[174:175], v[42:43], v[168:169], v[174:175] op_sel:[0,1,0] op_sel_hi:[1,1,1] neg_lo:[1,0,0] neg_hi:[1,0,0]
	v_fma_f32 v171, -v133, v170, v171
	v_pk_fma_f32 v[172:173], v[36:37], v[170:171], v[172:173] op_sel_hi:[1,0,1] neg_lo:[1,0,0] neg_hi:[1,0,0]
	v_pk_fma_f32 v[174:175], v[38:39], v[170:171], v[174:175] op_sel_hi:[1,0,1] neg_lo:[1,0,0] neg_hi:[1,0,0]
	v_pk_fma_f32 v[172:173], v[32:33], v[170:171], v[172:173] op_sel:[0,1,0] op_sel_hi:[1,1,1] neg_lo:[1,0,0] neg_hi:[1,0,0]
	v_pk_fma_f32 v[174:175], v[34:35], v[170:171], v[174:175] op_sel:[0,1,0] op_sel_hi:[1,1,1] neg_lo:[1,0,0] neg_hi:[1,0,0]
	v_fma_f32 v173, -v142, v172, v173
	v_pk_fma_f32 v[174:175], v[144:145], v[172:173], v[174:175] op_sel_hi:[1,0,1] neg_lo:[1,0,0] neg_hi:[1,0,0]
	v_pk_fma_f32 v[174:175], v[146:147], v[172:173], v[174:175] op_sel:[0,1,0] op_sel_hi:[1,1,1] neg_lo:[1,0,0] neg_hi:[1,0,0]
	v_fma_f32 v175, -v143, v174, v175
	ds_write2_b32 v192, v218, v161 offset1:16
	ds_write2_b32 v192, v162, v163 offset0:32 offset1:48
	ds_write2_b32 v192, v164, v165 offset0:64 offset1:80
	ds_write2_b32 v192, v166, v167 offset0:96 offset1:112
	ds_write2_b32 v192, v168, v169 offset0:128 offset1:144
	ds_write2_b32 v192, v170, v171 offset0:160 offset1:176
	ds_write2_b32 v192, v172, v173 offset0:192 offset1:208
	ds_write2_b32 v192, v174, v175 offset0:224 offset1:240
